# saddr-form LDS-DMA in K-loops: removes 74 v_lshl_add_u64 per iteration set
# speedup vs baseline: 1.0168x; 1.0168x over previous
; #define PG8_STAGE(bufoff, gbase, voff) do { _Pragma("unroll") for (int _i = 0; _i < 2; ++_i) \
;         __builtin_amdgcn_global_load_lds((const unsigned*)((const char*)(gbase) + (voff)[_i]), (LAS unsigned*)(lds + (bufoff) + ldsw + _i * 8192), 16, 0, 0); } while (0)
; #define PG8_LDA(dst, b, h) do { _Pragma("unroll") for (int m = 0; m < 4; ++m) _Pragma("unroll") for (int k = 0; k < 2; ++k) dst[m][k] = *(const LAS bf16x8*)(lds + PG8_SA(b, h) + aoff + m * 2048 + k * 1024); } while (0)
; #define PG8_LDB(dst, b, h) do { _Pragma("unroll") for (int n = 0; n < 2; ++n) _Pragma("unroll") for (int k = 0; k < 2; ++k) dst[n][k] = *(const LAS bf16x8*)(lds + PG8_SB(b, h) + boff + n * 2048 + k * 1024); } while (0)
; #define PG8_MMA(ai, bj, At, Bt) do { __builtin_amdgcn_s_setprio(1); _Pragma("unroll") for (int m = 0; m < 4; ++m) _Pragma("unroll") for (int n = 0; n < 2; ++n) _Pragma("unroll") for (int k = 0; k < 2; ++k) \
;         acc[ai][bj][m][n] = __builtin_amdgcn_mfma_f32_16x16x32_bf16(Bt[n][k], At[m][k], acc[ai][bj][m][n], 0, 0, 0); __builtin_amdgcn_s_setprio(0); } while (0)
; #define PG8_WAIT_V(n) asm volatile("s_waitcnt vmcnt(" #n ")" ::: "memory")
; #define PG8_WAIT_L(n) asm volatile("s_waitcnt lgkmcnt(" #n ")" ::: "memory")
; #define PG8_BAR __builtin_amdgcn_s_barrier()
; #define PG8_SCHED __builtin_amdgcn_sched_barrier(0)
; template <class Epi, class Sched>
; __device__ __forceinline__ void gemm_phase(LAS unsigned char* lds, const int K, const Sched& S, const Epi& E) {
;     ...
;             PG8_LDB(B0, 0, 0); PG8_LDB(B1, 0, 1); PG8_SCHED; PG8_LDA(At, 0, 0); PG8_STAGE(PG8_SA(1, 1), a1 + hstep, voffA);
;             PG8_WAIT_V(8); PG8_WAIT_L(0); PG8_BAR; PG8_MMA(0, 0, At, B0); PG8_MMA(0, 1, At, B1); PG8_BAR; PG8_SCHED;
;             PG8_LDA(At, 0, 1); PG8_STAGE(PG8_SB(0, 0), b2, voffB); PG8_STAGE(PG8_SB(0, 1), b2 + hstep, voffB); PG8_STAGE(PG8_SA(0, 0), a2, voffA);
;             PG8_WAIT_V(8); PG8_WAIT_L(0); PG8_BAR; PG8_MMA(1, 0, At, B0); PG8_MMA(1, 1, At, B1); PG8_BAR; PG8_SCHED;
.LBB0_403:
	s_add_u32 s14, s8, 0xfffc0080
	s_addc_u32 s15, s9, -1
	s_add_i32 s16, 0, 0x10000
	s_cmp_eq_u32 s13, 12
	s_cselect_b32 s55, s2, s15
	s_cselect_b32 s54, s4, s14
	v_add_u32_e32 v128, s16, v149
	s_cselect_b32 s39, s5, s12
	s_cselect_b32 s38, s10, s11
	s_add_i32 s17, 0, 0x14000
	ds_read_b128 v[158:161], v128
	ds_read_b128 v[162:165], v128 offset:1024
	ds_read_b128 v[184:187], v128 offset:2048
	ds_read_b128 v[188:191], v128 offset:3072
	v_add_u32_e32 v128, s17, v149
	ds_read_b128 v[192:195], v128
	ds_read_b128 v[196:199], v128 offset:1024
	ds_read_b128 v[200:203], v128 offset:2048
	ds_read_b128 v[204:207], v128 offset:3072
	s_add_i32 m0, s59, 0xc000
	ds_read_b128 v[208:211], v147
	ds_read_b128 v[212:215], v147 offset:1024
	ds_read_b128 v[216:219], v147 offset:2048
	ds_read_b128 v[220:223], v147 offset:3072
	ds_read_b128 v[224:227], v147 offset:4096
	ds_read_b128 v[228:231], v147 offset:5120
	ds_read_b128 v[232:235], v147 offset:6144
	ds_read_b128 v[236:239], v147 offset:7168
	global_load_lds_dwordx4 v154, s[8:9]
	s_add_i32 m0, s59, 0xe000
	s_nop 0
	global_load_lds_dwordx4 v156, s[8:9]
	s_waitcnt vmcnt(8)
	s_waitcnt lgkmcnt(0)
	s_barrier
	s_setprio 1
	s_waitcnt lgkmcnt(0)
	v_mfma_f32_16x16x32_bf16 v[124:127], v[158:161], v[208:211], v[124:127]
	v_mfma_f32_16x16x32_bf16 v[120:123], v[184:187], v[208:211], v[120:123]
	v_mfma_f32_16x16x32_bf16 v[108:111], v[158:161], v[216:219], v[108:111]
	v_mfma_f32_16x16x32_bf16 v[104:107], v[184:187], v[216:219], v[104:107]
	v_mfma_f32_16x16x32_bf16 v[92:95], v[158:161], v[224:227], v[92:95]
	v_mfma_f32_16x16x32_bf16 v[88:91], v[184:187], v[224:227], v[88:91]
	v_mfma_f32_16x16x32_bf16 v[76:79], v[158:161], v[232:235], v[76:79]
	v_mfma_f32_16x16x32_bf16 v[72:75], v[184:187], v[232:235], v[72:75]
	v_mfma_f32_16x16x32_bf16 v[124:127], v[162:165], v[212:215], v[124:127]
	v_mfma_f32_16x16x32_bf16 v[120:123], v[188:191], v[212:215], v[120:123]
	v_mfma_f32_16x16x32_bf16 v[108:111], v[162:165], v[220:223], v[108:111]
	v_mfma_f32_16x16x32_bf16 v[104:107], v[188:191], v[220:223], v[104:107]
	v_mfma_f32_16x16x32_bf16 v[92:95], v[162:165], v[228:231], v[92:95]
	v_mfma_f32_16x16x32_bf16 v[88:91], v[188:191], v[228:231], v[88:91]
	v_mfma_f32_16x16x32_bf16 v[76:79], v[162:165], v[236:239], v[76:79]
	v_mfma_f32_16x16x32_bf16 v[72:75], v[188:191], v[236:239], v[72:75]
	s_setprio 0
	s_setprio 1
	v_mfma_f32_16x16x32_bf16 v[116:119], v[192:195], v[208:211], v[116:119]
	v_mfma_f32_16x16x32_bf16 v[112:115], v[200:203], v[208:211], v[112:115]
	v_mfma_f32_16x16x32_bf16 v[100:103], v[192:195], v[216:219], v[100:103]
	v_mfma_f32_16x16x32_bf16 v[96:99], v[200:203], v[216:219], v[96:99]
	v_mfma_f32_16x16x32_bf16 v[84:87], v[192:195], v[224:227], v[84:87]
	v_mfma_f32_16x16x32_bf16 v[80:83], v[200:203], v[224:227], v[80:83]
	v_mfma_f32_16x16x32_bf16 v[68:71], v[192:195], v[232:235], v[68:71]
	v_mfma_f32_16x16x32_bf16 v[64:67], v[200:203], v[232:235], v[64:67]
	v_mfma_f32_16x16x32_bf16 v[116:119], v[196:199], v[212:215], v[116:119]
	v_mfma_f32_16x16x32_bf16 v[112:115], v[204:207], v[212:215], v[112:115]
	v_mfma_f32_16x16x32_bf16 v[100:103], v[196:199], v[220:223], v[100:103]
	v_mfma_f32_16x16x32_bf16 v[96:99], v[204:207], v[220:223], v[96:99]
	v_mfma_f32_16x16x32_bf16 v[84:87], v[196:199], v[228:231], v[84:87]
	v_mfma_f32_16x16x32_bf16 v[80:83], v[204:207], v[228:231], v[80:83]
	v_mfma_f32_16x16x32_bf16 v[68:71], v[196:199], v[236:239], v[68:71]
	v_mfma_f32_16x16x32_bf16 v[64:67], v[204:207], v[236:239], v[64:67]
	s_setprio 0
	s_barrier
	s_add_i32 s14, s16, s58
	s_mov_b32 m0, s14
	ds_read_b128 v[208:211], v147 offset:16384
	ds_read_b128 v[212:215], v147 offset:17408
	ds_read_b128 v[216:219], v147 offset:18432
	ds_read_b128 v[220:223], v147 offset:19456
	ds_read_b128 v[224:227], v147 offset:20480
	ds_read_b128 v[228:231], v147 offset:21504
	ds_read_b128 v[232:235], v147 offset:22528
	ds_read_b128 v[236:239], v147 offset:23552
	global_load_lds_dwordx4 v140, s[38:39]
	s_add_i32 m0, s14, 0x2000
	s_add_u32 s14, s38, 0x40000
	s_addc_u32 s15, s39, 0
	s_add_i32 s16, s17, s58
	global_load_lds_dwordx4 v144, s[38:39]
	s_mov_b32 m0, s16
	s_nop 0
	global_load_lds_dwordx4 v140, s[14:15]
	s_add_i32 m0, s16, 0x2000
	s_nop 0
	global_load_lds_dwordx4 v144, s[14:15]
	s_mov_b32 m0, s59
	s_nop 0
	global_load_lds_dwordx4 v138, s[54:55]
	s_mov_b32 m0, s60
	s_nop 0
	global_load_lds_dwordx4 v142, s[54:55]
	s_waitcnt vmcnt(8)
	s_waitcnt lgkmcnt(0)
	s_barrier
	s_setprio 1
	s_waitcnt lgkmcnt(0)
	v_mfma_f32_16x16x32_bf16 v[60:63], v[158:161], v[208:211], v[60:63]
	v_mfma_f32_16x16x32_bf16 v[56:59], v[184:187], v[208:211], v[56:59]
	v_mfma_f32_16x16x32_bf16 v[44:47], v[158:161], v[216:219], v[44:47]
	v_mfma_f32_16x16x32_bf16 v[40:43], v[184:187], v[216:219], v[40:43]
	v_mfma_f32_16x16x32_bf16 v[28:31], v[158:161], v[224:227], v[28:31]
	v_mfma_f32_16x16x32_bf16 v[24:27], v[184:187], v[224:227], v[24:27]
	v_mfma_f32_16x16x32_bf16 v[12:15], v[158:161], v[232:235], v[12:15]
	v_mfma_f32_16x16x32_bf16 v[8:11], v[184:187], v[232:235], v[8:11]
	v_mfma_f32_16x16x32_bf16 v[60:63], v[162:165], v[212:215], v[60:63]
	v_mfma_f32_16x16x32_bf16 v[56:59], v[188:191], v[212:215], v[56:59]
	v_mfma_f32_16x16x32_bf16 v[44:47], v[162:165], v[220:223], v[44:47]
	v_mfma_f32_16x16x32_bf16 v[40:43], v[188:191], v[220:223], v[40:43]
	v_mfma_f32_16x16x32_bf16 v[28:31], v[162:165], v[228:231], v[28:31]
	v_mfma_f32_16x16x32_bf16 v[24:27], v[188:191], v[228:231], v[24:27]
	v_mfma_f32_16x16x32_bf16 v[12:15], v[162:165], v[236:239], v[12:15]
	v_mfma_f32_16x16x32_bf16 v[8:11], v[188:191], v[236:239], v[8:11]
	s_setprio 0
	s_setprio 1
	v_mfma_f32_16x16x32_bf16 v[52:55], v[192:195], v[208:211], v[52:55]
	v_mfma_f32_16x16x32_bf16 v[48:51], v[200:203], v[208:211], v[48:51]
	v_mfma_f32_16x16x32_bf16 v[36:39], v[192:195], v[216:219], v[36:39]
	v_mfma_f32_16x16x32_bf16 v[32:35], v[200:203], v[216:219], v[32:35]
	v_mfma_f32_16x16x32_bf16 v[20:23], v[192:195], v[224:227], v[20:23]
	v_mfma_f32_16x16x32_bf16 v[16:19], v[200:203], v[224:227], v[16:19]
	v_mfma_f32_16x16x32_bf16 v[4:7], v[192:195], v[232:235], v[4:7]
	v_mfma_f32_16x16x32_bf16 v[0:3], v[200:203], v[232:235], v[0:3]
	v_mfma_f32_16x16x32_bf16 v[52:55], v[196:199], v[212:215], v[52:55]
	v_mfma_f32_16x16x32_bf16 v[48:51], v[204:207], v[212:215], v[48:51]
	v_mfma_f32_16x16x32_bf16 v[36:39], v[196:199], v[220:223], v[36:39]
	v_mfma_f32_16x16x32_bf16 v[32:35], v[204:207], v[220:223], v[32:35]
	v_mfma_f32_16x16x32_bf16 v[20:23], v[196:199], v[228:231], v[20:23]
	v_mfma_f32_16x16x32_bf16 v[16:19], v[204:207], v[228:231], v[16:19]
	v_mfma_f32_16x16x32_bf16 v[4:7], v[196:199], v[236:239], v[4:7]
	v_mfma_f32_16x16x32_bf16 v[0:3], v[204:207], v[236:239], v[0:3]
	s_setprio 0
	s_barrier
; #define PG8_STAGE(bufoff, gbase, voff) do { _Pragma("unroll") for (int _i = 0; _i < 2; ++_i) \
;         __builtin_amdgcn_global_load_lds((const unsigned*)((const char*)(gbase) + (voff)[_i]), (LAS unsigned*)(lds + (bufoff) + ldsw + _i * 8192), 16, 0, 0); } while (0)
; #define PG8_LDA(dst, b, h) do { _Pragma("unroll") for (int m = 0; m < 4; ++m) _Pragma("unroll") for (int k = 0; k < 2; ++k) dst[m][k] = *(const LAS bf16x8*)(lds + PG8_SA(b, h) + aoff + m * 2048 + k * 1024); } while (0)
; #define PG8_LDB(dst, b, h) do { _Pragma("unroll") for (int n = 0; n < 2; ++n) _Pragma("unroll") for (int k = 0; k < 2; ++k) dst[n][k] = *(const LAS bf16x8*)(lds + PG8_SB(b, h) + boff + n * 2048 + k * 1024); } while (0)
; #define PG8_MMA(ai, bj, At, Bt) do { __builtin_amdgcn_s_setprio(1); _Pragma("unroll") for (int m = 0; m < 4; ++m) _Pragma("unroll") for (int n = 0; n < 2; ++n) _Pragma("unroll") for (int k = 0; k < 2; ++k) \
;         acc[ai][bj][m][n] = __builtin_amdgcn_mfma_f32_16x16x32_bf16(Bt[n][k], At[m][k], acc[ai][bj][m][n], 0, 0, 0); __builtin_amdgcn_s_setprio(0); } while (0)
; #define PG8_WAIT_V(n) asm volatile("s_waitcnt vmcnt(" #n ")" ::: "memory")
; #define PG8_WAIT_L(n) asm volatile("s_waitcnt lgkmcnt(" #n ")" ::: "memory")
; #define PG8_BAR __builtin_amdgcn_s_barrier()
; #define PG8_SCHED __builtin_amdgcn_sched_barrier(0)
; template <class Epi, class Sched>
; __device__ __forceinline__ void gemm_phase(LAS unsigned char* lds, const int K, const Sched& S, const Epi& E) {
;     ...
;             PG8_LDB(B0, 1, 0); PG8_LDB(B1, 1, 1); PG8_SCHED; PG8_LDA(At, 1, 0); PG8_STAGE(PG8_SA(0, 1), a2 + hstep, voffA);
;             PG8_WAIT_V(8); PG8_WAIT_L(0); PG8_BAR; PG8_MMA(0, 0, At, B0); PG8_MMA(0, 1, At, B1); PG8_BAR; PG8_SCHED;
;             PG8_LDA(At, 1, 1); PG8_STAGE(PG8_SB(1, 0), b3, voffB); PG8_STAGE(PG8_SB(1, 1), b3 + hstep, voffB); PG8_STAGE(PG8_SA(1, 0), a3, voffA);
;             PG8_WAIT_V(8); PG8_WAIT_L(0); PG8_BAR; PG8_MMA(1, 0, At, B0); PG8_MMA(1, 1, At, B1); PG8_BAR; PG8_SCHED;
	s_add_i32 s16, 0, 0x18000
	v_add_u32_e32 v128, s16, v149
	s_add_i32 s17, 0, 0x1c000
	ds_read_b128 v[158:161], v128
	ds_read_b128 v[162:165], v128 offset:1024
	ds_read_b128 v[184:187], v128 offset:2048
	ds_read_b128 v[188:191], v128 offset:3072
	v_add_u32_e32 v128, s17, v149
	ds_read_b128 v[192:195], v128
	ds_read_b128 v[196:199], v128 offset:1024
	ds_read_b128 v[200:203], v128 offset:2048
	ds_read_b128 v[204:207], v128 offset:3072
	s_add_u32 s14, s54, 0x40000
	s_addc_u32 s15, s55, 0
	s_mov_b32 m0, s61
	ds_read_b128 v[208:211], v147 offset:32768
	ds_read_b128 v[212:215], v147 offset:33792
	ds_read_b128 v[216:219], v147 offset:34816
	ds_read_b128 v[220:223], v147 offset:35840
	ds_read_b128 v[224:227], v147 offset:36864
	ds_read_b128 v[228:231], v147 offset:37888
	ds_read_b128 v[232:235], v147 offset:38912
	ds_read_b128 v[236:239], v147 offset:39936
	global_load_lds_dwordx4 v138, s[14:15]
	s_mov_b32 m0, s62
	s_nop 0
	global_load_lds_dwordx4 v142, s[14:15]
	s_waitcnt vmcnt(8)
	s_waitcnt lgkmcnt(0)
	s_barrier
	s_setprio 1
	s_waitcnt lgkmcnt(0)
	v_mfma_f32_16x16x32_bf16 v[124:127], v[158:161], v[208:211], v[124:127]
	v_mfma_f32_16x16x32_bf16 v[120:123], v[184:187], v[208:211], v[120:123]
	v_mfma_f32_16x16x32_bf16 v[108:111], v[158:161], v[216:219], v[108:111]
	v_mfma_f32_16x16x32_bf16 v[104:107], v[184:187], v[216:219], v[104:107]
	v_mfma_f32_16x16x32_bf16 v[92:95], v[158:161], v[224:227], v[92:95]
	v_mfma_f32_16x16x32_bf16 v[88:91], v[184:187], v[224:227], v[88:91]
	v_mfma_f32_16x16x32_bf16 v[76:79], v[158:161], v[232:235], v[76:79]
	v_mfma_f32_16x16x32_bf16 v[72:75], v[184:187], v[232:235], v[72:75]
	v_mfma_f32_16x16x32_bf16 v[124:127], v[162:165], v[212:215], v[124:127]
	v_mfma_f32_16x16x32_bf16 v[120:123], v[188:191], v[212:215], v[120:123]
	v_mfma_f32_16x16x32_bf16 v[108:111], v[162:165], v[220:223], v[108:111]
	v_mfma_f32_16x16x32_bf16 v[104:107], v[188:191], v[220:223], v[104:107]
	v_mfma_f32_16x16x32_bf16 v[92:95], v[162:165], v[228:231], v[92:95]
	v_mfma_f32_16x16x32_bf16 v[88:91], v[188:191], v[228:231], v[88:91]
	v_mfma_f32_16x16x32_bf16 v[76:79], v[162:165], v[236:239], v[76:79]
	v_mfma_f32_16x16x32_bf16 v[72:75], v[188:191], v[236:239], v[72:75]
	s_setprio 0
	s_setprio 1
	v_mfma_f32_16x16x32_bf16 v[116:119], v[192:195], v[208:211], v[116:119]
	v_mfma_f32_16x16x32_bf16 v[112:115], v[200:203], v[208:211], v[112:115]
	v_mfma_f32_16x16x32_bf16 v[100:103], v[192:195], v[216:219], v[100:103]
	v_mfma_f32_16x16x32_bf16 v[96:99], v[200:203], v[216:219], v[96:99]
	v_mfma_f32_16x16x32_bf16 v[84:87], v[192:195], v[224:227], v[84:87]
	v_mfma_f32_16x16x32_bf16 v[80:83], v[200:203], v[224:227], v[80:83]
	v_mfma_f32_16x16x32_bf16 v[68:71], v[192:195], v[232:235], v[68:71]
	v_mfma_f32_16x16x32_bf16 v[64:67], v[200:203], v[232:235], v[64:67]
	v_mfma_f32_16x16x32_bf16 v[116:119], v[196:199], v[212:215], v[116:119]
	v_mfma_f32_16x16x32_bf16 v[112:115], v[204:207], v[212:215], v[112:115]
	v_mfma_f32_16x16x32_bf16 v[100:103], v[196:199], v[220:223], v[100:103]
	v_mfma_f32_16x16x32_bf16 v[96:99], v[204:207], v[220:223], v[96:99]
	v_mfma_f32_16x16x32_bf16 v[84:87], v[196:199], v[228:231], v[84:87]
	v_mfma_f32_16x16x32_bf16 v[80:83], v[204:207], v[228:231], v[80:83]
	v_mfma_f32_16x16x32_bf16 v[68:71], v[196:199], v[236:239], v[68:71]
	v_mfma_f32_16x16x32_bf16 v[64:67], v[204:207], v[236:239], v[64:67]
	s_setprio 0
	s_barrier
	s_add_i32 s14, s16, s58
	s_mov_b32 m0, s14
	ds_read_b128 v[208:211], v147 offset:49152
	ds_read_b128 v[212:215], v147 offset:50176
	ds_read_b128 v[216:219], v147 offset:51200
	ds_read_b128 v[220:223], v147 offset:52224
	ds_read_b128 v[224:227], v147 offset:53248
	ds_read_b128 v[228:231], v147 offset:54272
	ds_read_b128 v[232:235], v147 offset:55296
	ds_read_b128 v[236:239], v147 offset:56320
	s_add_u32 s100, s38, s36
	s_addc_u32 s101, s39, s37
	global_load_lds_dwordx4 v140, s[100:101]
	s_add_i32 m0, s14, 0x2000
	s_add_u32 s14, s38, 0x40080
	s_addc_u32 s15, s39, 0
	s_add_i32 s16, s17, s58
	s_add_u32 s100, s38, s36
	s_addc_u32 s101, s39, s37
	global_load_lds_dwordx4 v144, s[100:101]
	s_mov_b32 m0, s16
	s_nop 0
	global_load_lds_dwordx4 v140, s[14:15]
	s_add_i32 m0, s16, 0x2000
	s_nop 0
	global_load_lds_dwordx4 v144, s[14:15]
	s_mov_b32 m0, s64
	s_nop 0
	s_add_u32 s100, s54, s36
	s_addc_u32 s101, s55, s37
	global_load_lds_dwordx4 v138, s[100:101]
	s_mov_b32 m0, s65
	s_nop 0
	s_add_u32 s100, s54, s36
	s_addc_u32 s101, s55, s37
	global_load_lds_dwordx4 v142, s[100:101]
	s_waitcnt vmcnt(8)
	s_waitcnt lgkmcnt(0)
	s_barrier
	s_setprio 1
	s_waitcnt lgkmcnt(0)
	v_mfma_f32_16x16x32_bf16 v[60:63], v[158:161], v[208:211], v[60:63]
	v_mfma_f32_16x16x32_bf16 v[56:59], v[184:187], v[208:211], v[56:59]
	v_mfma_f32_16x16x32_bf16 v[44:47], v[158:161], v[216:219], v[44:47]
	v_mfma_f32_16x16x32_bf16 v[40:43], v[184:187], v[216:219], v[40:43]
	v_mfma_f32_16x16x32_bf16 v[28:31], v[158:161], v[224:227], v[28:31]
	v_mfma_f32_16x16x32_bf16 v[24:27], v[184:187], v[224:227], v[24:27]
	v_mfma_f32_16x16x32_bf16 v[12:15], v[158:161], v[232:235], v[12:15]
	v_mfma_f32_16x16x32_bf16 v[8:11], v[184:187], v[232:235], v[8:11]
	v_mfma_f32_16x16x32_bf16 v[60:63], v[162:165], v[212:215], v[60:63]
	v_mfma_f32_16x16x32_bf16 v[56:59], v[188:191], v[212:215], v[56:59]
	v_mfma_f32_16x16x32_bf16 v[44:47], v[162:165], v[220:223], v[44:47]
	v_mfma_f32_16x16x32_bf16 v[40:43], v[188:191], v[220:223], v[40:43]
	v_mfma_f32_16x16x32_bf16 v[28:31], v[162:165], v[228:231], v[28:31]
	v_mfma_f32_16x16x32_bf16 v[24:27], v[188:191], v[228:231], v[24:27]
	v_mfma_f32_16x16x32_bf16 v[12:15], v[162:165], v[236:239], v[12:15]
	v_mfma_f32_16x16x32_bf16 v[8:11], v[188:191], v[236:239], v[8:11]
	s_setprio 0
	s_setprio 1
	v_mfma_f32_16x16x32_bf16 v[52:55], v[192:195], v[208:211], v[52:55]
	v_mfma_f32_16x16x32_bf16 v[48:51], v[200:203], v[208:211], v[48:51]
	v_mfma_f32_16x16x32_bf16 v[36:39], v[192:195], v[216:219], v[36:39]
	v_mfma_f32_16x16x32_bf16 v[32:35], v[200:203], v[216:219], v[32:35]
	v_mfma_f32_16x16x32_bf16 v[20:23], v[192:195], v[224:227], v[20:23]
	v_mfma_f32_16x16x32_bf16 v[16:19], v[200:203], v[224:227], v[16:19]
	v_mfma_f32_16x16x32_bf16 v[4:7], v[192:195], v[232:235], v[4:7]
	v_mfma_f32_16x16x32_bf16 v[0:3], v[200:203], v[232:235], v[0:3]
	v_mfma_f32_16x16x32_bf16 v[52:55], v[196:199], v[212:215], v[52:55]
	v_mfma_f32_16x16x32_bf16 v[48:51], v[204:207], v[212:215], v[48:51]
	v_mfma_f32_16x16x32_bf16 v[36:39], v[196:199], v[220:223], v[36:39]
	v_mfma_f32_16x16x32_bf16 v[32:35], v[204:207], v[220:223], v[32:35]
	v_mfma_f32_16x16x32_bf16 v[20:23], v[196:199], v[228:231], v[20:23]
	v_mfma_f32_16x16x32_bf16 v[16:19], v[204:207], v[228:231], v[16:19]
	v_mfma_f32_16x16x32_bf16 v[4:7], v[196:199], v[236:239], v[4:7]
	v_mfma_f32_16x16x32_bf16 v[0:3], v[204:207], v[236:239], v[0:3]
	s_setprio 0
	s_barrier
	s_add_i32 s13, s13, 2
	s_add_u32 s8, s8, 0x100
	s_addc_u32 s9, s9, 0
	s_add_u32 s11, s11, 0x100
	s_addc_u32 s12, s12, 0
	s_cmp_gt_u32 s13, 13
	s_cbranch_scc0 .LBB0_403
	s_and_b64 vcc, exec, s[42:43]
	s_cbranch_vccz .LBB0_406
	s_barrier

; #define PG8_STAGE(bufoff, gbase, voff) do { _Pragma("unroll") for (int _i = 0; _i < 2; ++_i) \
;         __builtin_amdgcn_global_load_lds((const unsigned*)((const char*)(gbase) + (voff)[_i]), (LAS unsigned*)(lds + (bufoff) + ldsw + _i * 8192), 16, 0, 0); } while (0)
; #define PG8_LDA(dst, b, h) do { _Pragma("unroll") for (int m = 0; m < 4; ++m) _Pragma("unroll") for (int k = 0; k < 2; ++k) dst[m][k] = *(const LAS bf16x8*)(lds + PG8_SA(b, h) + aoff + m * 2048 + k * 1024); } while (0)
; #define PG8_LDB(dst, b, h) do { _Pragma("unroll") for (int n = 0; n < 2; ++n) _Pragma("unroll") for (int k = 0; k < 2; ++k) dst[n][k] = *(const LAS bf16x8*)(lds + PG8_SB(b, h) + boff + n * 2048 + k * 1024); } while (0)
; #define PG8_MMA(ai, bj, At, Bt) do { __builtin_amdgcn_s_setprio(1); _Pragma("unroll") for (int m = 0; m < 4; ++m) _Pragma("unroll") for (int n = 0; n < 2; ++n) _Pragma("unroll") for (int k = 0; k < 2; ++k) \
;         acc[ai][bj][m][n] = __builtin_amdgcn_mfma_f32_16x16x32_bf16(Bt[n][k], At[m][k], acc[ai][bj][m][n], 0, 0, 0); __builtin_amdgcn_s_setprio(0); } while (0)
; #define PG8_WAIT_V(n) asm volatile("s_waitcnt vmcnt(" #n ")" ::: "memory")
; #define PG8_WAIT_L(n) asm volatile("s_waitcnt lgkmcnt(" #n ")" ::: "memory")
; #define PG8_BAR __builtin_amdgcn_s_barrier()
; #define PG8_SCHED __builtin_amdgcn_sched_barrier(0)
; template <class Epi, class Sched>
; __device__ __forceinline__ void gemm_phase(LAS unsigned char* lds, const int K, const Sched& S, const Epi& E) {
;     ...
;             PG8_LDB(B0, 0, 0); PG8_LDB(B1, 0, 1); PG8_SCHED; PG8_LDA(At, 0, 0); PG8_STAGE(PG8_SA(1, 1), a1 + hstep, voffA);
;             PG8_WAIT_V(8); PG8_WAIT_L(0); PG8_BAR; PG8_MMA(0, 0, At, B0); PG8_MMA(0, 1, At, B1); PG8_BAR; PG8_SCHED;
;             PG8_LDA(At, 0, 1); PG8_STAGE(PG8_SB(0, 0), b2, voffB); PG8_STAGE(PG8_SB(0, 1), b2 + hstep, voffB); PG8_STAGE(PG8_SA(0, 0), a2, voffA);
;             PG8_WAIT_V(8); PG8_WAIT_L(0); PG8_BAR; PG8_MMA(1, 0, At, B0); PG8_MMA(1, 1, At, B1); PG8_BAR; PG8_SCHED;
.LBB0_511:
	s_add_i32 s14, s8, 0xfaf9e080
	s_cmp_lg_u32 s13, 60
	s_cselect_b32 s14, s14, 0
	s_add_u32 s40, s28, s14
	s_addc_u32 s41, s29, 0
	s_add_i32 s15, 0, 0x10000
	s_add_u32 s38, s34, s14
	s_addc_u32 s39, s35, 0
	s_add_i32 s16, 0, 0x14000
	v_add_u32_e32 v164, s15, v145
	v_add_u32_e32 v180, s16, v145
	ds_read_b128 v[152:155], v164
	ds_read_b128 v[156:159], v164 offset:1024
	ds_read_b128 v[160:163], v164 offset:2048
	ds_read_b128 v[164:167], v164 offset:3072
	ds_read_b128 v[184:187], v180
	ds_read_b128 v[188:191], v180 offset:1024
	ds_read_b128 v[192:195], v180 offset:2048
	ds_read_b128 v[196:199], v180 offset:3072
	v_lshl_add_u64 v[180:181], v[146:147], 0, s[8:9]
	s_add_i32 m0, s2, 0xc000
	ds_read_b128 v[200:203], v151
	ds_read_b128 v[204:207], v151 offset:1024
	ds_read_b128 v[208:211], v151 offset:2048
	ds_read_b128 v[212:215], v151 offset:3072
	ds_read_b128 v[216:219], v151 offset:4096
	ds_read_b128 v[220:223], v151 offset:5120
	ds_read_b128 v[224:227], v151 offset:6144
	ds_read_b128 v[228:231], v151 offset:7168
	global_load_lds_dwordx4 v[180:181], off
	v_lshl_add_u64 v[180:181], v[148:149], 0, s[8:9]
	s_add_i32 m0, s2, 0xe000
	s_nop 0
	global_load_lds_dwordx4 v[180:181], off
	s_waitcnt vmcnt(8)
	s_waitcnt lgkmcnt(0)
	s_barrier
	s_setprio 1
	s_waitcnt lgkmcnt(0)
	v_mfma_f32_16x16x32_bf16 v[124:127], v[152:155], v[200:203], v[124:127]
	v_mfma_f32_16x16x32_bf16 v[120:123], v[160:163], v[200:203], v[120:123]
	v_mfma_f32_16x16x32_bf16 v[108:111], v[152:155], v[208:211], v[108:111]
	v_mfma_f32_16x16x32_bf16 v[104:107], v[160:163], v[208:211], v[104:107]
	v_mfma_f32_16x16x32_bf16 v[92:95], v[152:155], v[216:219], v[92:95]
	v_mfma_f32_16x16x32_bf16 v[88:91], v[160:163], v[216:219], v[88:91]
	v_mfma_f32_16x16x32_bf16 v[76:79], v[152:155], v[224:227], v[76:79]
	v_mfma_f32_16x16x32_bf16 v[72:75], v[160:163], v[224:227], v[72:75]
	v_mfma_f32_16x16x32_bf16 v[124:127], v[156:159], v[204:207], v[124:127]
	v_mfma_f32_16x16x32_bf16 v[120:123], v[164:167], v[204:207], v[120:123]
	v_mfma_f32_16x16x32_bf16 v[108:111], v[156:159], v[212:215], v[108:111]
	v_mfma_f32_16x16x32_bf16 v[104:107], v[164:167], v[212:215], v[104:107]
	v_mfma_f32_16x16x32_bf16 v[92:95], v[156:159], v[220:223], v[92:95]
	v_mfma_f32_16x16x32_bf16 v[88:91], v[164:167], v[220:223], v[88:91]
	v_mfma_f32_16x16x32_bf16 v[76:79], v[156:159], v[228:231], v[76:79]
	v_mfma_f32_16x16x32_bf16 v[72:75], v[164:167], v[228:231], v[72:75]
	s_setprio 0
	s_setprio 1
	v_mfma_f32_16x16x32_bf16 v[116:119], v[184:187], v[200:203], v[116:119]
	v_mfma_f32_16x16x32_bf16 v[112:115], v[192:195], v[200:203], v[112:115]
	v_mfma_f32_16x16x32_bf16 v[100:103], v[184:187], v[208:211], v[100:103]
	v_mfma_f32_16x16x32_bf16 v[96:99], v[192:195], v[208:211], v[96:99]
	v_mfma_f32_16x16x32_bf16 v[84:87], v[184:187], v[216:219], v[84:87]
	v_mfma_f32_16x16x32_bf16 v[80:83], v[192:195], v[216:219], v[80:83]
	v_mfma_f32_16x16x32_bf16 v[68:71], v[184:187], v[224:227], v[68:71]
	v_mfma_f32_16x16x32_bf16 v[64:67], v[192:195], v[224:227], v[64:67]
	v_mfma_f32_16x16x32_bf16 v[116:119], v[188:191], v[204:207], v[116:119]
	v_mfma_f32_16x16x32_bf16 v[112:115], v[196:199], v[204:207], v[112:115]
	v_mfma_f32_16x16x32_bf16 v[100:103], v[188:191], v[212:215], v[100:103]
	v_mfma_f32_16x16x32_bf16 v[96:99], v[196:199], v[212:215], v[96:99]
	v_mfma_f32_16x16x32_bf16 v[84:87], v[188:191], v[220:223], v[84:87]
	v_mfma_f32_16x16x32_bf16 v[80:83], v[196:199], v[220:223], v[80:83]
	v_mfma_f32_16x16x32_bf16 v[68:71], v[188:191], v[228:231], v[68:71]
	v_mfma_f32_16x16x32_bf16 v[64:67], v[196:199], v[228:231], v[64:67]
	s_setprio 0
	s_barrier
	s_add_i32 s14, s15, s1
	s_mov_b32 m0, s14
	ds_read_b128 v[200:203], v151 offset:16384
	ds_read_b128 v[204:207], v151 offset:17408
	ds_read_b128 v[208:211], v151 offset:18432
	ds_read_b128 v[212:215], v151 offset:19456
	ds_read_b128 v[216:219], v151 offset:20480
	ds_read_b128 v[220:223], v151 offset:21504
	ds_read_b128 v[224:227], v151 offset:22528
	ds_read_b128 v[228:231], v151 offset:23552
	global_load_lds_dwordx4 v128, s[38:39]
	s_add_i32 m0, s14, 0x2000
	s_add_u32 s14, s38, 0x100000
	s_addc_u32 s15, s39, 0
	s_add_i32 s16, s16, s1
	global_load_lds_dwordx4 v138, s[38:39]
	s_mov_b32 m0, s16
	s_nop 0
	global_load_lds_dwordx4 v128, s[14:15]
	s_add_i32 m0, s16, 0x2000
	s_nop 0
	global_load_lds_dwordx4 v138, s[14:15]
	s_mov_b32 m0, s2
	s_nop 0
	global_load_lds_dwordx4 v142, s[40:41]
	s_mov_b32 m0, s3
	s_nop 0
	global_load_lds_dwordx4 v140, s[40:41]
	s_waitcnt vmcnt(8)
	s_waitcnt lgkmcnt(0)
	s_barrier
; #define PG8_STAGE(bufoff, gbase, voff) do { _Pragma("unroll") for (int _i = 0; _i < 2; ++_i) \
;         __builtin_amdgcn_global_load_lds((const unsigned*)((const char*)(gbase) + (voff)[_i]), (LAS unsigned*)(lds + (bufoff) + ldsw + _i * 8192), 16, 0, 0); } while (0)
; #define PG8_LDA(dst, b, h) do { _Pragma("unroll") for (int m = 0; m < 4; ++m) _Pragma("unroll") for (int k = 0; k < 2; ++k) dst[m][k] = *(const LAS bf16x8*)(lds + PG8_SA(b, h) + aoff + m * 2048 + k * 1024); } while (0)
; #define PG8_LDB(dst, b, h) do { _Pragma("unroll") for (int n = 0; n < 2; ++n) _Pragma("unroll") for (int k = 0; k < 2; ++k) dst[n][k] = *(const LAS bf16x8*)(lds + PG8_SB(b, h) + boff + n * 2048 + k * 1024); } while (0)
; #define PG8_MMA(ai, bj, At, Bt) do { __builtin_amdgcn_s_setprio(1); _Pragma("unroll") for (int m = 0; m < 4; ++m) _Pragma("unroll") for (int n = 0; n < 2; ++n) _Pragma("unroll") for (int k = 0; k < 2; ++k) \
;         acc[ai][bj][m][n] = __builtin_amdgcn_mfma_f32_16x16x32_bf16(Bt[n][k], At[m][k], acc[ai][bj][m][n], 0, 0, 0); __builtin_amdgcn_s_setprio(0); } while (0)
; #define PG8_WAIT_V(n) asm volatile("s_waitcnt vmcnt(" #n ")" ::: "memory")
; #define PG8_WAIT_L(n) asm volatile("s_waitcnt lgkmcnt(" #n ")" ::: "memory")
; #define PG8_BAR __builtin_amdgcn_s_barrier()
; #define PG8_SCHED __builtin_amdgcn_sched_barrier(0)
; template <class Epi, class Sched>
; __device__ __forceinline__ void gemm_phase(LAS unsigned char* lds, const int K, const Sched& S, const Epi& E) {
;     ...
;             PG8_WAIT_V(8); PG8_WAIT_L(0); PG8_BAR; PG8_MMA(1, 0, At, B0); PG8_MMA(1, 1, At, B1); PG8_BAR; PG8_SCHED;
;             PG8_LDB(B0, 1, 0); PG8_LDB(B1, 1, 1); PG8_SCHED; PG8_LDA(At, 1, 0); PG8_STAGE(PG8_SA(0, 1), a2 + hstep, voffA);
;             PG8_WAIT_V(8); PG8_WAIT_L(0); PG8_BAR; PG8_MMA(0, 0, At, B0); PG8_MMA(0, 1, At, B1); PG8_BAR; PG8_SCHED;
;             PG8_LDA(At, 1, 1); PG8_STAGE(PG8_SB(1, 0), b3, voffB); PG8_STAGE(PG8_SB(1, 1), b3 + hstep, voffB); PG8_STAGE(PG8_SA(1, 0), a3, voffA);
	s_setprio 1
	s_waitcnt lgkmcnt(0)
	v_mfma_f32_16x16x32_bf16 v[60:63], v[152:155], v[200:203], v[60:63]
	v_mfma_f32_16x16x32_bf16 v[56:59], v[160:163], v[200:203], v[56:59]
	v_mfma_f32_16x16x32_bf16 v[44:47], v[152:155], v[208:211], v[44:47]
	v_mfma_f32_16x16x32_bf16 v[40:43], v[160:163], v[208:211], v[40:43]
	v_mfma_f32_16x16x32_bf16 v[28:31], v[152:155], v[216:219], v[28:31]
	v_mfma_f32_16x16x32_bf16 v[24:27], v[160:163], v[216:219], v[24:27]
	v_mfma_f32_16x16x32_bf16 v[12:15], v[152:155], v[224:227], v[12:15]
	v_mfma_f32_16x16x32_bf16 v[8:11], v[160:163], v[224:227], v[8:11]
	v_mfma_f32_16x16x32_bf16 v[60:63], v[156:159], v[204:207], v[60:63]
	v_mfma_f32_16x16x32_bf16 v[56:59], v[164:167], v[204:207], v[56:59]
	v_mfma_f32_16x16x32_bf16 v[44:47], v[156:159], v[212:215], v[44:47]
	v_mfma_f32_16x16x32_bf16 v[40:43], v[164:167], v[212:215], v[40:43]
	v_mfma_f32_16x16x32_bf16 v[28:31], v[156:159], v[220:223], v[28:31]
	v_mfma_f32_16x16x32_bf16 v[24:27], v[164:167], v[220:223], v[24:27]
	v_mfma_f32_16x16x32_bf16 v[12:15], v[156:159], v[228:231], v[12:15]
	v_mfma_f32_16x16x32_bf16 v[8:11], v[164:167], v[228:231], v[8:11]
	s_setprio 0
	s_setprio 1
	v_mfma_f32_16x16x32_bf16 v[52:55], v[184:187], v[200:203], v[52:55]
	v_mfma_f32_16x16x32_bf16 v[48:51], v[192:195], v[200:203], v[48:51]
	v_mfma_f32_16x16x32_bf16 v[36:39], v[184:187], v[208:211], v[36:39]
	v_mfma_f32_16x16x32_bf16 v[32:35], v[192:195], v[208:211], v[32:35]
	v_mfma_f32_16x16x32_bf16 v[20:23], v[184:187], v[216:219], v[20:23]
	v_mfma_f32_16x16x32_bf16 v[16:19], v[192:195], v[216:219], v[16:19]
	v_mfma_f32_16x16x32_bf16 v[4:7], v[184:187], v[224:227], v[4:7]
	v_mfma_f32_16x16x32_bf16 v[0:3], v[192:195], v[224:227], v[0:3]
	v_mfma_f32_16x16x32_bf16 v[52:55], v[188:191], v[204:207], v[52:55]
	v_mfma_f32_16x16x32_bf16 v[48:51], v[196:199], v[204:207], v[48:51]
	v_mfma_f32_16x16x32_bf16 v[36:39], v[188:191], v[212:215], v[36:39]
	v_mfma_f32_16x16x32_bf16 v[32:35], v[196:199], v[212:215], v[32:35]
	v_mfma_f32_16x16x32_bf16 v[20:23], v[188:191], v[220:223], v[20:23]
	v_mfma_f32_16x16x32_bf16 v[16:19], v[196:199], v[220:223], v[16:19]
	v_mfma_f32_16x16x32_bf16 v[4:7], v[188:191], v[228:231], v[4:7]
	v_mfma_f32_16x16x32_bf16 v[0:3], v[196:199], v[228:231], v[0:3]
	s_setprio 0
	s_barrier
	s_add_i32 s16, 0, 0x18000
	s_add_i32 s17, 0, 0x1c000
	v_add_u32_e32 v164, s16, v145
	v_add_u32_e32 v196, s17, v145
	ds_read_b128 v[152:155], v164
	ds_read_b128 v[156:159], v164 offset:1024
	ds_read_b128 v[160:163], v164 offset:2048
	ds_read_b128 v[164:167], v164 offset:3072
	ds_read_b128 v[184:187], v196
	ds_read_b128 v[188:191], v196 offset:1024
	ds_read_b128 v[192:195], v196 offset:2048
	ds_read_b128 v[196:199], v196 offset:3072
	s_add_u32 s14, s40, 0x100000
	s_addc_u32 s15, s41, 0
	s_mov_b32 m0, s4
	ds_read_b128 v[200:203], v151 offset:32768
	ds_read_b128 v[204:207], v151 offset:33792
	ds_read_b128 v[208:211], v151 offset:34816
	ds_read_b128 v[212:215], v151 offset:35840
	ds_read_b128 v[216:219], v151 offset:36864
	ds_read_b128 v[220:223], v151 offset:37888
	ds_read_b128 v[224:227], v151 offset:38912
	ds_read_b128 v[228:231], v151 offset:39936
	global_load_lds_dwordx4 v142, s[14:15]
	s_mov_b32 m0, s5
	s_nop 0
	global_load_lds_dwordx4 v140, s[14:15]
	s_waitcnt vmcnt(8)
	s_waitcnt lgkmcnt(0)
	s_barrier
	s_setprio 1
	s_waitcnt lgkmcnt(0)
	v_mfma_f32_16x16x32_bf16 v[124:127], v[152:155], v[200:203], v[124:127]
	v_mfma_f32_16x16x32_bf16 v[120:123], v[160:163], v[200:203], v[120:123]
	v_mfma_f32_16x16x32_bf16 v[108:111], v[152:155], v[208:211], v[108:111]
	v_mfma_f32_16x16x32_bf16 v[104:107], v[160:163], v[208:211], v[104:107]
	v_mfma_f32_16x16x32_bf16 v[92:95], v[152:155], v[216:219], v[92:95]
	v_mfma_f32_16x16x32_bf16 v[88:91], v[160:163], v[216:219], v[88:91]
	v_mfma_f32_16x16x32_bf16 v[76:79], v[152:155], v[224:227], v[76:79]
	v_mfma_f32_16x16x32_bf16 v[72:75], v[160:163], v[224:227], v[72:75]
	v_mfma_f32_16x16x32_bf16 v[124:127], v[156:159], v[204:207], v[124:127]
	v_mfma_f32_16x16x32_bf16 v[120:123], v[164:167], v[204:207], v[120:123]
	v_mfma_f32_16x16x32_bf16 v[108:111], v[156:159], v[212:215], v[108:111]
	v_mfma_f32_16x16x32_bf16 v[104:107], v[164:167], v[212:215], v[104:107]
	v_mfma_f32_16x16x32_bf16 v[92:95], v[156:159], v[220:223], v[92:95]
	v_mfma_f32_16x16x32_bf16 v[88:91], v[164:167], v[220:223], v[88:91]
	v_mfma_f32_16x16x32_bf16 v[76:79], v[156:159], v[228:231], v[76:79]
	v_mfma_f32_16x16x32_bf16 v[72:75], v[164:167], v[228:231], v[72:75]
	s_setprio 0
	s_setprio 1
	v_mfma_f32_16x16x32_bf16 v[116:119], v[184:187], v[200:203], v[116:119]
	v_mfma_f32_16x16x32_bf16 v[112:115], v[192:195], v[200:203], v[112:115]
	v_mfma_f32_16x16x32_bf16 v[100:103], v[184:187], v[208:211], v[100:103]
	v_mfma_f32_16x16x32_bf16 v[96:99], v[192:195], v[208:211], v[96:99]
	v_mfma_f32_16x16x32_bf16 v[84:87], v[184:187], v[216:219], v[84:87]
	v_mfma_f32_16x16x32_bf16 v[80:83], v[192:195], v[216:219], v[80:83]
	v_mfma_f32_16x16x32_bf16 v[68:71], v[184:187], v[224:227], v[68:71]
	v_mfma_f32_16x16x32_bf16 v[64:67], v[192:195], v[224:227], v[64:67]
	v_mfma_f32_16x16x32_bf16 v[116:119], v[188:191], v[204:207], v[116:119]
	v_mfma_f32_16x16x32_bf16 v[112:115], v[196:199], v[204:207], v[112:115]
	v_mfma_f32_16x16x32_bf16 v[100:103], v[188:191], v[212:215], v[100:103]
	v_mfma_f32_16x16x32_bf16 v[96:99], v[196:199], v[212:215], v[96:99]
	v_mfma_f32_16x16x32_bf16 v[84:87], v[188:191], v[220:223], v[84:87]
	v_mfma_f32_16x16x32_bf16 v[80:83], v[196:199], v[220:223], v[80:83]
	v_mfma_f32_16x16x32_bf16 v[68:71], v[188:191], v[228:231], v[68:71]
	v_mfma_f32_16x16x32_bf16 v[64:67], v[196:199], v[228:231], v[64:67]
	s_setprio 0
	s_barrier
; #define PG8_STAGE(bufoff, gbase, voff) do { _Pragma("unroll") for (int _i = 0; _i < 2; ++_i) \
;         __builtin_amdgcn_global_load_lds((const unsigned*)((const char*)(gbase) + (voff)[_i]), (LAS unsigned*)(lds + (bufoff) + ldsw + _i * 8192), 16, 0, 0); } while (0)
; #define PG8_LDA(dst, b, h) do { _Pragma("unroll") for (int m = 0; m < 4; ++m) _Pragma("unroll") for (int k = 0; k < 2; ++k) dst[m][k] = *(const LAS bf16x8*)(lds + PG8_SA(b, h) + aoff + m * 2048 + k * 1024); } while (0)
; #define PG8_MMA(ai, bj, At, Bt) do { __builtin_amdgcn_s_setprio(1); _Pragma("unroll") for (int m = 0; m < 4; ++m) _Pragma("unroll") for (int n = 0; n < 2; ++n) _Pragma("unroll") for (int k = 0; k < 2; ++k) \
;         acc[ai][bj][m][n] = __builtin_amdgcn_mfma_f32_16x16x32_bf16(Bt[n][k], At[m][k], acc[ai][bj][m][n], 0, 0, 0); __builtin_amdgcn_s_setprio(0); } while (0)
; #define PG8_WAIT_V(n) asm volatile("s_waitcnt vmcnt(" #n ")" ::: "memory")
; #define PG8_WAIT_L(n) asm volatile("s_waitcnt lgkmcnt(" #n ")" ::: "memory")
; #define PG8_BAR __builtin_amdgcn_s_barrier()
; #define PG8_SCHED __builtin_amdgcn_sched_barrier(0)
; template <class Epi, class Sched>
; __device__ __forceinline__ void gemm_phase(LAS unsigned char* lds, const int K, const Sched& S, const Epi& E) {
;     ...
;             PG8_LDA(At, 1, 1); PG8_STAGE(PG8_SB(1, 0), b3, voffB); PG8_STAGE(PG8_SB(1, 1), b3 + hstep, voffB); PG8_STAGE(PG8_SA(1, 0), a3, voffA);
;             PG8_WAIT_V(8); PG8_WAIT_L(0); PG8_BAR; PG8_MMA(1, 0, At, B0); PG8_MMA(1, 1, At, B1); PG8_BAR; PG8_SCHED;
	s_add_i32 s14, s16, s1
	s_mov_b32 m0, s14
	ds_read_b128 v[200:203], v151 offset:49152
	ds_read_b128 v[204:207], v151 offset:50176
	ds_read_b128 v[208:211], v151 offset:51200
	ds_read_b128 v[212:215], v151 offset:52224
	ds_read_b128 v[216:219], v151 offset:53248
	ds_read_b128 v[220:223], v151 offset:54272
	ds_read_b128 v[224:227], v151 offset:55296
	ds_read_b128 v[228:231], v151 offset:56320
	s_add_u32 s100, s38, s36
	s_addc_u32 s101, s39, s37
	global_load_lds_dwordx4 v128, s[100:101]
	s_add_i32 m0, s14, 0x2000
	s_add_u32 s14, s38, 0x100080
	s_addc_u32 s15, s39, 0
	s_add_i32 s16, s17, s1
	s_add_u32 s100, s38, s36
	s_addc_u32 s101, s39, s37
	global_load_lds_dwordx4 v138, s[100:101]
	s_mov_b32 m0, s16
	s_nop 0
	global_load_lds_dwordx4 v128, s[14:15]
	s_add_i32 m0, s16, 0x2000
	s_nop 0
	global_load_lds_dwordx4 v138, s[14:15]
	s_mov_b32 m0, s11
	s_nop 0
	s_add_u32 s100, s40, s36
	s_addc_u32 s101, s41, s37
	global_load_lds_dwordx4 v142, s[100:101]
	s_mov_b32 m0, s12
	s_nop 0
	s_add_u32 s100, s40, s36
	s_addc_u32 s101, s41, s37
	global_load_lds_dwordx4 v140, s[100:101]
	s_waitcnt vmcnt(8)
	s_waitcnt lgkmcnt(0)
	s_barrier
	s_setprio 1
	s_waitcnt lgkmcnt(0)
	v_mfma_f32_16x16x32_bf16 v[60:63], v[152:155], v[200:203], v[60:63]
	v_mfma_f32_16x16x32_bf16 v[56:59], v[160:163], v[200:203], v[56:59]
	v_mfma_f32_16x16x32_bf16 v[44:47], v[152:155], v[208:211], v[44:47]
	v_mfma_f32_16x16x32_bf16 v[40:43], v[160:163], v[208:211], v[40:43]
	v_mfma_f32_16x16x32_bf16 v[28:31], v[152:155], v[216:219], v[28:31]
	v_mfma_f32_16x16x32_bf16 v[24:27], v[160:163], v[216:219], v[24:27]
	v_mfma_f32_16x16x32_bf16 v[12:15], v[152:155], v[224:227], v[12:15]
	v_mfma_f32_16x16x32_bf16 v[8:11], v[160:163], v[224:227], v[8:11]
	v_mfma_f32_16x16x32_bf16 v[60:63], v[156:159], v[204:207], v[60:63]
	v_mfma_f32_16x16x32_bf16 v[56:59], v[164:167], v[204:207], v[56:59]
	v_mfma_f32_16x16x32_bf16 v[44:47], v[156:159], v[212:215], v[44:47]
	v_mfma_f32_16x16x32_bf16 v[40:43], v[164:167], v[212:215], v[40:43]
	v_mfma_f32_16x16x32_bf16 v[28:31], v[156:159], v[220:223], v[28:31]
	v_mfma_f32_16x16x32_bf16 v[24:27], v[164:167], v[220:223], v[24:27]
	v_mfma_f32_16x16x32_bf16 v[12:15], v[156:159], v[228:231], v[12:15]
	v_mfma_f32_16x16x32_bf16 v[8:11], v[164:167], v[228:231], v[8:11]
	s_setprio 0
	s_setprio 1
	v_mfma_f32_16x16x32_bf16 v[52:55], v[184:187], v[200:203], v[52:55]
	v_mfma_f32_16x16x32_bf16 v[48:51], v[192:195], v[200:203], v[48:51]
	v_mfma_f32_16x16x32_bf16 v[36:39], v[184:187], v[208:211], v[36:39]
	v_mfma_f32_16x16x32_bf16 v[32:35], v[192:195], v[208:211], v[32:35]
	v_mfma_f32_16x16x32_bf16 v[20:23], v[184:187], v[216:219], v[20:23]
	v_mfma_f32_16x16x32_bf16 v[16:19], v[192:195], v[216:219], v[16:19]
	v_mfma_f32_16x16x32_bf16 v[4:7], v[184:187], v[224:227], v[4:7]
	v_mfma_f32_16x16x32_bf16 v[0:3], v[192:195], v[224:227], v[0:3]
	v_mfma_f32_16x16x32_bf16 v[52:55], v[188:191], v[204:207], v[52:55]
	v_mfma_f32_16x16x32_bf16 v[48:51], v[196:199], v[204:207], v[48:51]
	v_mfma_f32_16x16x32_bf16 v[36:39], v[188:191], v[212:215], v[36:39]
	v_mfma_f32_16x16x32_bf16 v[32:35], v[196:199], v[212:215], v[32:35]
	v_mfma_f32_16x16x32_bf16 v[20:23], v[188:191], v[220:223], v[20:23]
	v_mfma_f32_16x16x32_bf16 v[16:19], v[196:199], v[220:223], v[16:19]
	v_mfma_f32_16x16x32_bf16 v[4:7], v[188:191], v[228:231], v[4:7]
	v_mfma_f32_16x16x32_bf16 v[0:3], v[196:199], v[228:231], v[0:3]
	s_setprio 0
	s_barrier
	s_add_i32 s13, s13, 2
	s_add_u32 s8, s8, 0x100
	s_addc_u32 s9, s9, 0
	s_cmp_gt_u32 s13, 61
	s_cbranch_scc0 .LBB0_511
	s_cmpk_lt_u32 s0, 0x100
	s_cbranch_scc0 .LBB0_514
	s_barrier

; #define PG8_STAGE(bufoff, gbase, voff) do { _Pragma("unroll") for (int _i = 0; _i < 2; ++_i) \
;         __builtin_amdgcn_global_load_lds((const unsigned*)((const char*)(gbase) + (voff)[_i]), (LAS unsigned*)(lds + (bufoff) + ldsw + _i * 8192), 16, 0, 0); } while (0)
; #define PG8_LDA(dst, b, h) do { _Pragma("unroll") for (int m = 0; m < 4; ++m) _Pragma("unroll") for (int k = 0; k < 2; ++k) dst[m][k] = *(const LAS bf16x8*)(lds + PG8_SA(b, h) + aoff + m * 2048 + k * 1024); } while (0)
; #define PG8_LDB(dst, b, h) do { _Pragma("unroll") for (int n = 0; n < 2; ++n) _Pragma("unroll") for (int k = 0; k < 2; ++k) dst[n][k] = *(const LAS bf16x8*)(lds + PG8_SB(b, h) + boff + n * 2048 + k * 1024); } while (0)
; #define PG8_MMA(ai, bj, At, Bt) do { __builtin_amdgcn_s_setprio(1); _Pragma("unroll") for (int m = 0; m < 4; ++m) _Pragma("unroll") for (int n = 0; n < 2; ++n) _Pragma("unroll") for (int k = 0; k < 2; ++k) \
;         acc[ai][bj][m][n] = __builtin_amdgcn_mfma_f32_16x16x32_bf16(Bt[n][k], At[m][k], acc[ai][bj][m][n], 0, 0, 0); __builtin_amdgcn_s_setprio(0); } while (0)
; #define PG8_WAIT_V(n) asm volatile("s_waitcnt vmcnt(" #n ")" ::: "memory")
; #define PG8_WAIT_L(n) asm volatile("s_waitcnt lgkmcnt(" #n ")" ::: "memory")
; #define PG8_BAR __builtin_amdgcn_s_barrier()
; #define PG8_SCHED __builtin_amdgcn_sched_barrier(0)
; template <class Epi, class Sched>
; __device__ __forceinline__ void gemm_phase(LAS unsigned char* lds, const int K, const Sched& S, const Epi& E) {
;     ...
;             PG8_LDB(B0, 0, 0); PG8_LDB(B1, 0, 1); PG8_SCHED; PG8_LDA(At, 0, 0); PG8_STAGE(PG8_SA(1, 1), a1 + hstep, voffA);
;             PG8_WAIT_V(8); PG8_WAIT_L(0); PG8_BAR; PG8_MMA(0, 0, At, B0); PG8_MMA(0, 1, At, B1); PG8_BAR; PG8_SCHED;
;             PG8_LDA(At, 0, 1); PG8_STAGE(PG8_SB(0, 0), b2, voffB); PG8_STAGE(PG8_SB(0, 1), b2 + hstep, voffB); PG8_STAGE(PG8_SA(0, 0), a2, voffA);
;             PG8_WAIT_V(8); PG8_WAIT_L(0); PG8_BAR; PG8_MMA(1, 0, At, B0); PG8_MMA(1, 1, At, B1); PG8_BAR; PG8_SCHED;
.LBB0_812:
	s_add_i32 s16, s15, 2
	s_add_u32 s50, s8, 0x100
	s_addc_u32 s51, s9, 0
	s_add_i32 s17, 0, 0x10000
	s_cmp_eq_u32 s12, s15
	s_cselect_b32 s55, s4, s51
	s_cselect_b32 s54, s5, s50
	s_cselect_b32 s53, s10, s14
	s_cselect_b32 s52, s11, s13
	s_add_i32 s15, 0, 0x14000
	v_add_u32_e32 v158, s17, v164
	v_add_u32_e32 v162, s15, v164
	ds_read_b128 v[146:149], v158
	ds_read_b128 v[150:153], v158 offset:1024
	ds_read_b128 v[154:157], v158 offset:2048
	ds_read_b128 v[158:161], v158 offset:3072
	ds_read_b128 v[184:187], v162
	ds_read_b128 v[188:191], v162 offset:1024
	ds_read_b128 v[192:195], v162 offset:2048
	ds_read_b128 v[196:199], v162 offset:3072
	v_lshl_add_u64 v[162:163], s[8:9], 0, v[142:143]
	s_add_i32 m0, s26, 0xc000
	ds_read_b128 v[200:203], v166
	ds_read_b128 v[204:207], v166 offset:1024
	ds_read_b128 v[208:211], v166 offset:2048
	ds_read_b128 v[212:215], v166 offset:3072
	ds_read_b128 v[216:219], v166 offset:4096
	ds_read_b128 v[220:223], v166 offset:5120
	ds_read_b128 v[224:227], v166 offset:6144
	ds_read_b128 v[228:231], v166 offset:7168
	global_load_lds_dwordx4 v[162:163], off
	v_lshl_add_u64 v[162:163], s[8:9], 0, v[144:145]
	s_add_i32 m0, s26, 0xe000
	s_nop 0
	global_load_lds_dwordx4 v[162:163], off
	s_waitcnt vmcnt(8)
	s_waitcnt lgkmcnt(0)
	s_barrier
	s_setprio 1
	s_waitcnt lgkmcnt(0)
	v_mfma_f32_16x16x32_bf16 v[124:127], v[146:149], v[200:203], v[124:127]
	v_mfma_f32_16x16x32_bf16 v[92:95], v[154:157], v[200:203], v[92:95]
	v_mfma_f32_16x16x32_bf16 v[120:123], v[146:149], v[208:211], v[120:123]
	v_mfma_f32_16x16x32_bf16 v[88:91], v[154:157], v[208:211], v[88:91]
	v_mfma_f32_16x16x32_bf16 v[116:119], v[146:149], v[216:219], v[116:119]
	v_mfma_f32_16x16x32_bf16 v[84:87], v[154:157], v[216:219], v[84:87]
	v_mfma_f32_16x16x32_bf16 v[112:115], v[146:149], v[224:227], v[112:115]
	v_mfma_f32_16x16x32_bf16 v[80:83], v[154:157], v[224:227], v[80:83]
	v_mfma_f32_16x16x32_bf16 v[124:127], v[150:153], v[204:207], v[124:127]
	v_mfma_f32_16x16x32_bf16 v[92:95], v[158:161], v[204:207], v[92:95]
	v_mfma_f32_16x16x32_bf16 v[120:123], v[150:153], v[212:215], v[120:123]
	v_mfma_f32_16x16x32_bf16 v[88:91], v[158:161], v[212:215], v[88:91]
	v_mfma_f32_16x16x32_bf16 v[116:119], v[150:153], v[220:223], v[116:119]
	v_mfma_f32_16x16x32_bf16 v[84:87], v[158:161], v[220:223], v[84:87]
	v_mfma_f32_16x16x32_bf16 v[112:115], v[150:153], v[228:231], v[112:115]
	v_mfma_f32_16x16x32_bf16 v[80:83], v[158:161], v[228:231], v[80:83]
	s_setprio 0
	s_setprio 1
	v_mfma_f32_16x16x32_bf16 v[64:67], v[184:187], v[200:203], v[64:67]
	v_mfma_f32_16x16x32_bf16 v[40:43], v[192:195], v[200:203], v[40:43]
	v_mfma_f32_16x16x32_bf16 v[56:59], v[184:187], v[208:211], v[56:59]
	v_mfma_f32_16x16x32_bf16 v[32:35], v[192:195], v[208:211], v[32:35]
	v_mfma_f32_16x16x32_bf16 v[52:55], v[184:187], v[216:219], v[52:55]
	v_mfma_f32_16x16x32_bf16 v[24:27], v[192:195], v[216:219], v[24:27]
	v_mfma_f32_16x16x32_bf16 v[48:51], v[184:187], v[224:227], v[48:51]
	v_mfma_f32_16x16x32_bf16 v[16:19], v[192:195], v[224:227], v[16:19]
	v_mfma_f32_16x16x32_bf16 v[64:67], v[188:191], v[204:207], v[64:67]
	v_mfma_f32_16x16x32_bf16 v[40:43], v[196:199], v[204:207], v[40:43]
	v_mfma_f32_16x16x32_bf16 v[56:59], v[188:191], v[212:215], v[56:59]
	v_mfma_f32_16x16x32_bf16 v[32:35], v[196:199], v[212:215], v[32:35]
	v_mfma_f32_16x16x32_bf16 v[52:55], v[188:191], v[220:223], v[52:55]
	v_mfma_f32_16x16x32_bf16 v[24:27], v[196:199], v[220:223], v[24:27]
	v_mfma_f32_16x16x32_bf16 v[48:51], v[188:191], v[228:231], v[48:51]
	v_mfma_f32_16x16x32_bf16 v[16:19], v[196:199], v[228:231], v[16:19]
	s_setprio 0
	s_barrier
	s_add_i32 s8, s17, s3
	s_mov_b32 m0, s8
	ds_read_b128 v[200:203], v166 offset:16384
	ds_read_b128 v[204:207], v166 offset:17408
	ds_read_b128 v[208:211], v166 offset:18432
	ds_read_b128 v[212:215], v166 offset:19456
	ds_read_b128 v[216:219], v166 offset:20480
	ds_read_b128 v[220:223], v166 offset:21504
	ds_read_b128 v[224:227], v166 offset:22528
	ds_read_b128 v[228:231], v166 offset:23552
	global_load_lds_dwordx4 v128, s[52:53]
	s_add_i32 m0, s8, 0x2000
	s_add_u32 s8, s52, 0x50000
	s_addc_u32 s9, s53, 0
	s_add_i32 s15, s15, s3
	global_load_lds_dwordx4 v138, s[52:53]
	s_mov_b32 m0, s15
	s_nop 0
	global_load_lds_dwordx4 v128, s[8:9]
	s_add_i32 m0, s15, 0x2000
	s_nop 0
	global_load_lds_dwordx4 v138, s[8:9]
	s_mov_b32 m0, s26
	s_nop 0
	global_load_lds_dwordx4 v128, s[54:55]
	s_mov_b32 m0, s27
	s_nop 0
	global_load_lds_dwordx4 v138, s[54:55]
	s_waitcnt vmcnt(8)
	s_waitcnt lgkmcnt(0)
	s_barrier
; #define PG8_STAGE(bufoff, gbase, voff) do { _Pragma("unroll") for (int _i = 0; _i < 2; ++_i) \
;         __builtin_amdgcn_global_load_lds((const unsigned*)((const char*)(gbase) + (voff)[_i]), (LAS unsigned*)(lds + (bufoff) + ldsw + _i * 8192), 16, 0, 0); } while (0)
; #define PG8_LDA(dst, b, h) do { _Pragma("unroll") for (int m = 0; m < 4; ++m) _Pragma("unroll") for (int k = 0; k < 2; ++k) dst[m][k] = *(const LAS bf16x8*)(lds + PG8_SA(b, h) + aoff + m * 2048 + k * 1024); } while (0)
; #define PG8_LDB(dst, b, h) do { _Pragma("unroll") for (int n = 0; n < 2; ++n) _Pragma("unroll") for (int k = 0; k < 2; ++k) dst[n][k] = *(const LAS bf16x8*)(lds + PG8_SB(b, h) + boff + n * 2048 + k * 1024); } while (0)
; #define PG8_MMA(ai, bj, At, Bt) do { __builtin_amdgcn_s_setprio(1); _Pragma("unroll") for (int m = 0; m < 4; ++m) _Pragma("unroll") for (int n = 0; n < 2; ++n) _Pragma("unroll") for (int k = 0; k < 2; ++k) \
;         acc[ai][bj][m][n] = __builtin_amdgcn_mfma_f32_16x16x32_bf16(Bt[n][k], At[m][k], acc[ai][bj][m][n], 0, 0, 0); __builtin_amdgcn_s_setprio(0); } while (0)
; #define PG8_WAIT_V(n) asm volatile("s_waitcnt vmcnt(" #n ")" ::: "memory")
; #define PG8_WAIT_L(n) asm volatile("s_waitcnt lgkmcnt(" #n ")" ::: "memory")
; #define PG8_BAR __builtin_amdgcn_s_barrier()
; #define PG8_SCHED __builtin_amdgcn_sched_barrier(0)
; template <class Epi, class Sched>
; __device__ __forceinline__ void gemm_phase(LAS unsigned char* lds, const int K, const Sched& S, const Epi& E) {
;     ...
;             PG8_WAIT_V(8); PG8_WAIT_L(0); PG8_BAR; PG8_MMA(1, 0, At, B0); PG8_MMA(1, 1, At, B1); PG8_BAR; PG8_SCHED;
;             PG8_LDB(B0, 1, 0); PG8_LDB(B1, 1, 1); PG8_SCHED; PG8_LDA(At, 1, 0); PG8_STAGE(PG8_SA(0, 1), a2 + hstep, voffA);
;             PG8_WAIT_V(8); PG8_WAIT_L(0); PG8_BAR; PG8_MMA(0, 0, At, B0); PG8_MMA(0, 1, At, B1); PG8_BAR; PG8_SCHED;
;             PG8_LDA(At, 1, 1); PG8_STAGE(PG8_SB(1, 0), b3, voffB); PG8_STAGE(PG8_SB(1, 1), b3 + hstep, voffB); PG8_STAGE(PG8_SA(1, 0), a3, voffA);
	s_setprio 1
	s_waitcnt lgkmcnt(0)
	v_mfma_f32_16x16x32_bf16 v[108:111], v[146:149], v[200:203], v[108:111]
	v_mfma_f32_16x16x32_bf16 v[76:79], v[154:157], v[200:203], v[76:79]
	v_mfma_f32_16x16x32_bf16 v[104:107], v[146:149], v[208:211], v[104:107]
	v_mfma_f32_16x16x32_bf16 v[72:75], v[154:157], v[208:211], v[72:75]
	v_mfma_f32_16x16x32_bf16 v[100:103], v[146:149], v[216:219], v[100:103]
	v_mfma_f32_16x16x32_bf16 v[68:71], v[154:157], v[216:219], v[68:71]
	v_mfma_f32_16x16x32_bf16 v[96:99], v[146:149], v[224:227], v[96:99]
	v_mfma_f32_16x16x32_bf16 v[60:63], v[154:157], v[224:227], v[60:63]
	v_mfma_f32_16x16x32_bf16 v[108:111], v[150:153], v[204:207], v[108:111]
	v_mfma_f32_16x16x32_bf16 v[76:79], v[158:161], v[204:207], v[76:79]
	v_mfma_f32_16x16x32_bf16 v[104:107], v[150:153], v[212:215], v[104:107]
	v_mfma_f32_16x16x32_bf16 v[72:75], v[158:161], v[212:215], v[72:75]
	v_mfma_f32_16x16x32_bf16 v[100:103], v[150:153], v[220:223], v[100:103]
	v_mfma_f32_16x16x32_bf16 v[68:71], v[158:161], v[220:223], v[68:71]
	v_mfma_f32_16x16x32_bf16 v[96:99], v[150:153], v[228:231], v[96:99]
	v_mfma_f32_16x16x32_bf16 v[60:63], v[158:161], v[228:231], v[60:63]
	s_setprio 0
	s_setprio 1
	v_mfma_f32_16x16x32_bf16 v[44:47], v[184:187], v[200:203], v[44:47]
	v_mfma_f32_16x16x32_bf16 v[12:15], v[192:195], v[200:203], v[12:15]
	v_mfma_f32_16x16x32_bf16 v[36:39], v[184:187], v[208:211], v[36:39]
	v_mfma_f32_16x16x32_bf16 v[8:11], v[192:195], v[208:211], v[8:11]
	v_mfma_f32_16x16x32_bf16 v[28:31], v[184:187], v[216:219], v[28:31]
	v_mfma_f32_16x16x32_bf16 v[4:7], v[192:195], v[216:219], v[4:7]
	v_mfma_f32_16x16x32_bf16 v[20:23], v[184:187], v[224:227], v[20:23]
	v_mfma_f32_16x16x32_bf16 v[0:3], v[192:195], v[224:227], v[0:3]
	v_mfma_f32_16x16x32_bf16 v[44:47], v[188:191], v[204:207], v[44:47]
	v_mfma_f32_16x16x32_bf16 v[12:15], v[196:199], v[204:207], v[12:15]
	v_mfma_f32_16x16x32_bf16 v[36:39], v[188:191], v[212:215], v[36:39]
	v_mfma_f32_16x16x32_bf16 v[8:11], v[196:199], v[212:215], v[8:11]
	v_mfma_f32_16x16x32_bf16 v[28:31], v[188:191], v[220:223], v[28:31]
	v_mfma_f32_16x16x32_bf16 v[4:7], v[196:199], v[220:223], v[4:7]
	v_mfma_f32_16x16x32_bf16 v[20:23], v[188:191], v[228:231], v[20:23]
	v_mfma_f32_16x16x32_bf16 v[0:3], v[196:199], v[228:231], v[0:3]
	s_setprio 0
	s_barrier
	s_add_i32 s15, 0, 0x18000
	s_add_i32 s17, 0, 0x1c000
	v_add_u32_e32 v158, s15, v164
	v_add_u32_e32 v167, s17, v164
	ds_read_b128 v[146:149], v158
	ds_read_b128 v[150:153], v158 offset:1024
	ds_read_b128 v[154:157], v158 offset:2048
	ds_read_b128 v[158:161], v158 offset:3072
	ds_read_b128 v[184:187], v167
	ds_read_b128 v[188:191], v167 offset:1024
	ds_read_b128 v[192:195], v167 offset:2048
	ds_read_b128 v[196:199], v167 offset:3072
	s_add_u32 s8, s54, 0x50000
	s_addc_u32 s9, s55, 0
	s_mov_b32 m0, s56
	ds_read_b128 v[200:203], v166 offset:32768
	ds_read_b128 v[204:207], v166 offset:33792
	ds_read_b128 v[208:211], v166 offset:34816
	ds_read_b128 v[212:215], v166 offset:35840
	ds_read_b128 v[216:219], v166 offset:36864
	ds_read_b128 v[220:223], v166 offset:37888
	ds_read_b128 v[224:227], v166 offset:38912
	ds_read_b128 v[228:231], v166 offset:39936
	global_load_lds_dwordx4 v128, s[8:9]
	s_mov_b32 m0, s57
	s_nop 0
	global_load_lds_dwordx4 v138, s[8:9]
	s_waitcnt vmcnt(8)
	s_waitcnt lgkmcnt(0)
	s_barrier
	s_setprio 1
	s_waitcnt lgkmcnt(0)
	v_mfma_f32_16x16x32_bf16 v[124:127], v[146:149], v[200:203], v[124:127]
	v_mfma_f32_16x16x32_bf16 v[92:95], v[154:157], v[200:203], v[92:95]
	v_mfma_f32_16x16x32_bf16 v[120:123], v[146:149], v[208:211], v[120:123]
	v_mfma_f32_16x16x32_bf16 v[88:91], v[154:157], v[208:211], v[88:91]
	v_mfma_f32_16x16x32_bf16 v[116:119], v[146:149], v[216:219], v[116:119]
	v_mfma_f32_16x16x32_bf16 v[84:87], v[154:157], v[216:219], v[84:87]
	v_mfma_f32_16x16x32_bf16 v[112:115], v[146:149], v[224:227], v[112:115]
	v_mfma_f32_16x16x32_bf16 v[80:83], v[154:157], v[224:227], v[80:83]
	v_mfma_f32_16x16x32_bf16 v[124:127], v[150:153], v[204:207], v[124:127]
	v_mfma_f32_16x16x32_bf16 v[92:95], v[158:161], v[204:207], v[92:95]
	v_mfma_f32_16x16x32_bf16 v[120:123], v[150:153], v[212:215], v[120:123]
	v_mfma_f32_16x16x32_bf16 v[88:91], v[158:161], v[212:215], v[88:91]
	v_mfma_f32_16x16x32_bf16 v[116:119], v[150:153], v[220:223], v[116:119]
	v_mfma_f32_16x16x32_bf16 v[84:87], v[158:161], v[220:223], v[84:87]
	v_mfma_f32_16x16x32_bf16 v[112:115], v[150:153], v[228:231], v[112:115]
	v_mfma_f32_16x16x32_bf16 v[80:83], v[158:161], v[228:231], v[80:83]
	s_setprio 0
	s_setprio 1
	v_mfma_f32_16x16x32_bf16 v[64:67], v[184:187], v[200:203], v[64:67]
	v_mfma_f32_16x16x32_bf16 v[40:43], v[192:195], v[200:203], v[40:43]
	v_mfma_f32_16x16x32_bf16 v[56:59], v[184:187], v[208:211], v[56:59]
	v_mfma_f32_16x16x32_bf16 v[32:35], v[192:195], v[208:211], v[32:35]
	v_mfma_f32_16x16x32_bf16 v[52:55], v[184:187], v[216:219], v[52:55]
	v_mfma_f32_16x16x32_bf16 v[24:27], v[192:195], v[216:219], v[24:27]
	v_mfma_f32_16x16x32_bf16 v[48:51], v[184:187], v[224:227], v[48:51]
	v_mfma_f32_16x16x32_bf16 v[16:19], v[192:195], v[224:227], v[16:19]
	v_mfma_f32_16x16x32_bf16 v[64:67], v[188:191], v[204:207], v[64:67]
	v_mfma_f32_16x16x32_bf16 v[40:43], v[196:199], v[204:207], v[40:43]
	v_mfma_f32_16x16x32_bf16 v[56:59], v[188:191], v[212:215], v[56:59]
	v_mfma_f32_16x16x32_bf16 v[32:35], v[196:199], v[212:215], v[32:35]
	v_mfma_f32_16x16x32_bf16 v[52:55], v[188:191], v[220:223], v[52:55]
	v_mfma_f32_16x16x32_bf16 v[24:27], v[196:199], v[220:223], v[24:27]
	v_mfma_f32_16x16x32_bf16 v[48:51], v[188:191], v[228:231], v[48:51]
	v_mfma_f32_16x16x32_bf16 v[16:19], v[196:199], v[228:231], v[16:19]
	s_setprio 0
	s_barrier
; #define PG8_STAGE(bufoff, gbase, voff) do { _Pragma("unroll") for (int _i = 0; _i < 2; ++_i) \
;         __builtin_amdgcn_global_load_lds((const unsigned*)((const char*)(gbase) + (voff)[_i]), (LAS unsigned*)(lds + (bufoff) + ldsw + _i * 8192), 16, 0, 0); } while (0)
; #define PG8_LDA(dst, b, h) do { _Pragma("unroll") for (int m = 0; m < 4; ++m) _Pragma("unroll") for (int k = 0; k < 2; ++k) dst[m][k] = *(const LAS bf16x8*)(lds + PG8_SA(b, h) + aoff + m * 2048 + k * 1024); } while (0)
; #define PG8_MMA(ai, bj, At, Bt) do { __builtin_amdgcn_s_setprio(1); _Pragma("unroll") for (int m = 0; m < 4; ++m) _Pragma("unroll") for (int n = 0; n < 2; ++n) _Pragma("unroll") for (int k = 0; k < 2; ++k) \
;         acc[ai][bj][m][n] = __builtin_amdgcn_mfma_f32_16x16x32_bf16(Bt[n][k], At[m][k], acc[ai][bj][m][n], 0, 0, 0); __builtin_amdgcn_s_setprio(0); } while (0)
; #define PG8_WAIT_V(n) asm volatile("s_waitcnt vmcnt(" #n ")" ::: "memory")
; #define PG8_WAIT_L(n) asm volatile("s_waitcnt lgkmcnt(" #n ")" ::: "memory")
; #define PG8_BAR __builtin_amdgcn_s_barrier()
; #define PG8_SCHED __builtin_amdgcn_sched_barrier(0)
; template <class Epi, class Sched>
; __device__ __forceinline__ void gemm_phase(LAS unsigned char* lds, const int K, const Sched& S, const Epi& E) {
;     ...
;             PG8_LDA(At, 1, 1); PG8_STAGE(PG8_SB(1, 0), b3, voffB); PG8_STAGE(PG8_SB(1, 1), b3 + hstep, voffB); PG8_STAGE(PG8_SA(1, 0), a3, voffA);
;             PG8_WAIT_V(8); PG8_WAIT_L(0); PG8_BAR; PG8_MMA(1, 0, At, B0); PG8_MMA(1, 1, At, B1); PG8_BAR; PG8_SCHED;
	s_add_i32 s8, s15, s3
	s_mov_b32 m0, s8
	ds_read_b128 v[200:203], v166 offset:49152
	ds_read_b128 v[204:207], v166 offset:50176
	ds_read_b128 v[208:211], v166 offset:51200
	ds_read_b128 v[212:215], v166 offset:52224
	ds_read_b128 v[216:219], v166 offset:53248
	ds_read_b128 v[220:223], v166 offset:54272
	ds_read_b128 v[224:227], v166 offset:55296
	ds_read_b128 v[228:231], v166 offset:56320
	s_add_u32 s100, s52, s36
	s_addc_u32 s101, s53, s37
	global_load_lds_dwordx4 v128, s[100:101]
	s_add_i32 m0, s8, 0x2000
	s_add_u32 s8, s52, 0x50080
	s_addc_u32 s9, s53, 0
	s_add_i32 s15, s17, s3
	s_add_u32 s100, s52, s36
	s_addc_u32 s101, s53, s37
	global_load_lds_dwordx4 v138, s[100:101]
	s_mov_b32 m0, s15
	s_nop 0
	global_load_lds_dwordx4 v128, s[8:9]
	s_add_i32 m0, s15, 0x2000
	s_nop 0
	global_load_lds_dwordx4 v138, s[8:9]
	s_mov_b32 m0, s58
	s_nop 0
	s_add_u32 s100, s54, s36
	s_addc_u32 s101, s55, s37
	global_load_lds_dwordx4 v128, s[100:101]
	s_mov_b32 m0, s59
	s_nop 0
	s_add_u32 s100, s54, s36
	s_addc_u32 s101, s55, s37
	global_load_lds_dwordx4 v138, s[100:101]
	s_waitcnt vmcnt(8)
	s_waitcnt lgkmcnt(0)
	s_barrier
	s_setprio 1
	s_waitcnt lgkmcnt(0)
	v_mfma_f32_16x16x32_bf16 v[108:111], v[146:149], v[200:203], v[108:111]
	v_mfma_f32_16x16x32_bf16 v[76:79], v[154:157], v[200:203], v[76:79]
	v_mfma_f32_16x16x32_bf16 v[104:107], v[146:149], v[208:211], v[104:107]
	v_mfma_f32_16x16x32_bf16 v[72:75], v[154:157], v[208:211], v[72:75]
	v_mfma_f32_16x16x32_bf16 v[100:103], v[146:149], v[216:219], v[100:103]
	v_mfma_f32_16x16x32_bf16 v[68:71], v[154:157], v[216:219], v[68:71]
	v_mfma_f32_16x16x32_bf16 v[96:99], v[146:149], v[224:227], v[96:99]
	v_mfma_f32_16x16x32_bf16 v[60:63], v[154:157], v[224:227], v[60:63]
	v_mfma_f32_16x16x32_bf16 v[108:111], v[150:153], v[204:207], v[108:111]
	v_mfma_f32_16x16x32_bf16 v[76:79], v[158:161], v[204:207], v[76:79]
	v_mfma_f32_16x16x32_bf16 v[104:107], v[150:153], v[212:215], v[104:107]
	v_mfma_f32_16x16x32_bf16 v[72:75], v[158:161], v[212:215], v[72:75]
	v_mfma_f32_16x16x32_bf16 v[100:103], v[150:153], v[220:223], v[100:103]
	v_mfma_f32_16x16x32_bf16 v[68:71], v[158:161], v[220:223], v[68:71]
	v_mfma_f32_16x16x32_bf16 v[96:99], v[150:153], v[228:231], v[96:99]
	v_mfma_f32_16x16x32_bf16 v[60:63], v[158:161], v[228:231], v[60:63]
	s_setprio 0
	s_setprio 1
	v_mfma_f32_16x16x32_bf16 v[44:47], v[184:187], v[200:203], v[44:47]
	v_mfma_f32_16x16x32_bf16 v[12:15], v[192:195], v[200:203], v[12:15]
	v_mfma_f32_16x16x32_bf16 v[36:39], v[184:187], v[208:211], v[36:39]
	v_mfma_f32_16x16x32_bf16 v[8:11], v[192:195], v[208:211], v[8:11]
	v_mfma_f32_16x16x32_bf16 v[28:31], v[184:187], v[216:219], v[28:31]
	v_mfma_f32_16x16x32_bf16 v[4:7], v[192:195], v[216:219], v[4:7]
	v_mfma_f32_16x16x32_bf16 v[20:23], v[184:187], v[224:227], v[20:23]
	v_mfma_f32_16x16x32_bf16 v[0:3], v[192:195], v[224:227], v[0:3]
	v_mfma_f32_16x16x32_bf16 v[44:47], v[188:191], v[204:207], v[44:47]
	v_mfma_f32_16x16x32_bf16 v[12:15], v[196:199], v[204:207], v[12:15]
	v_mfma_f32_16x16x32_bf16 v[36:39], v[188:191], v[212:215], v[36:39]
	v_mfma_f32_16x16x32_bf16 v[8:11], v[196:199], v[212:215], v[8:11]
	v_mfma_f32_16x16x32_bf16 v[28:31], v[188:191], v[220:223], v[28:31]
	v_mfma_f32_16x16x32_bf16 v[4:7], v[196:199], v[220:223], v[4:7]
	v_mfma_f32_16x16x32_bf16 v[20:23], v[188:191], v[228:231], v[20:23]
	v_mfma_f32_16x16x32_bf16 v[0:3], v[196:199], v[228:231], v[0:3]
	s_setprio 0
	s_barrier
	s_add_u32 s13, s13, 0x100
	s_addc_u32 s14, s14, 0
	s_cmp_ge_i32 s16, s2
	s_mov_b64 s[8:9], s[50:51]
	s_mov_b32 s15, s16
	s_cbranch_scc0 .LBB0_812
	s_and_b64 vcc, exec, s[40:41]
	s_cbranch_vccz .LBB0_815
	s_barrier

; #define PG8_STAGE(bufoff, gbase, voff) do { _Pragma("unroll") for (int _i = 0; _i < 2; ++_i) \
;         __builtin_amdgcn_global_load_lds((const unsigned*)((const char*)(gbase) + (voff)[_i]), (LAS unsigned*)(lds + (bufoff) + ldsw + _i * 8192), 16, 0, 0); } while (0)
; #define PG8_LDA(dst, b, h) do { _Pragma("unroll") for (int m = 0; m < 4; ++m) _Pragma("unroll") for (int k = 0; k < 2; ++k) dst[m][k] = *(const LAS bf16x8*)(lds + PG8_SA(b, h) + aoff + m * 2048 + k * 1024); } while (0)
; #define PG8_LDB(dst, b, h) do { _Pragma("unroll") for (int n = 0; n < 2; ++n) _Pragma("unroll") for (int k = 0; k < 2; ++k) dst[n][k] = *(const LAS bf16x8*)(lds + PG8_SB(b, h) + boff + n * 2048 + k * 1024); } while (0)
; #define PG8_MMA(ai, bj, At, Bt) do { __builtin_amdgcn_s_setprio(1); _Pragma("unroll") for (int m = 0; m < 4; ++m) _Pragma("unroll") for (int n = 0; n < 2; ++n) _Pragma("unroll") for (int k = 0; k < 2; ++k) \
;         acc[ai][bj][m][n] = __builtin_amdgcn_mfma_f32_16x16x32_bf16(Bt[n][k], At[m][k], acc[ai][bj][m][n], 0, 0, 0); __builtin_amdgcn_s_setprio(0); } while (0)
; #define PG8_WAIT_V(n) asm volatile("s_waitcnt vmcnt(" #n ")" ::: "memory")
; #define PG8_WAIT_L(n) asm volatile("s_waitcnt lgkmcnt(" #n ")" ::: "memory")
; #define PG8_BAR __builtin_amdgcn_s_barrier()
; #define PG8_SCHED __builtin_amdgcn_sched_barrier(0)
; template <class Epi, class Sched>
; __device__ __forceinline__ void gemm_phase(LAS unsigned char* lds, const int K, const Sched& S, const Epi& E) {
;     ...
;             PG8_LDB(B0, 0, 0); PG8_LDB(B1, 0, 1); PG8_SCHED; PG8_LDA(At, 0, 0); PG8_STAGE(PG8_SA(1, 1), a1 + hstep, voffA);
;             PG8_WAIT_V(8); PG8_WAIT_L(0); PG8_BAR; PG8_MMA(0, 0, At, B0); PG8_MMA(0, 1, At, B1); PG8_BAR; PG8_SCHED;
;             PG8_LDA(At, 0, 1); PG8_STAGE(PG8_SB(0, 0), b2, voffB); PG8_STAGE(PG8_SB(0, 1), b2 + hstep, voffB); PG8_STAGE(PG8_SA(0, 0), a2, voffA);
;             PG8_WAIT_V(8); PG8_WAIT_L(0); PG8_BAR; PG8_MMA(1, 0, At, B0); PG8_MMA(1, 1, At, B1); PG8_BAR; PG8_SCHED;
.LBB0_963:
	s_add_u32 s5, s56, 0xfffc0080
	s_addc_u32 s9, s57, -1
	s_add_i32 s10, 0, 0x10000
	s_cmp_eq_u32 s4, 12
	s_cselect_b32 s61, s53, s9
	s_cselect_b32 s60, s52, s5
	v_add_u32_e32 v150, s10, v153
	s_cselect_b32 s59, s55, s2
	s_cselect_b32 s58, s54, s1
	s_add_i32 s5, 0, 0x14000
	ds_read_b128 v[156:159], v150
	ds_read_b128 v[160:163], v150 offset:1024
	ds_read_b128 v[164:167], v150 offset:2048
	ds_read_b128 v[180:183], v150 offset:3072
	v_add_u32_e32 v150, s5, v153
	ds_read_b128 v[184:187], v150
	ds_read_b128 v[188:191], v150 offset:1024
	ds_read_b128 v[192:195], v150 offset:2048
	ds_read_b128 v[196:199], v150 offset:3072
	s_add_i32 m0, s66, 0xc000
	ds_read_b128 v[200:203], v154
	ds_read_b128 v[204:207], v154 offset:1024
	ds_read_b128 v[208:211], v154 offset:2048
	ds_read_b128 v[212:215], v154 offset:3072
	ds_read_b128 v[216:219], v154 offset:4096
	ds_read_b128 v[220:223], v154 offset:5120
	ds_read_b128 v[224:227], v154 offset:6144
	ds_read_b128 v[228:231], v154 offset:7168
	global_load_lds_dwordx4 v146, s[56:57]
	s_add_i32 m0, s66, 0xe000
	s_nop 0
	global_load_lds_dwordx4 v148, s[56:57]
	s_waitcnt vmcnt(8)
	s_waitcnt lgkmcnt(0)
	s_barrier
	s_setprio 1
	s_waitcnt lgkmcnt(0)
	v_mfma_f32_16x16x32_bf16 v[124:127], v[156:159], v[200:203], v[124:127]
	v_mfma_f32_16x16x32_bf16 v[116:119], v[164:167], v[200:203], v[116:119]
	v_mfma_f32_16x16x32_bf16 v[108:111], v[156:159], v[208:211], v[108:111]
	v_mfma_f32_16x16x32_bf16 v[100:103], v[164:167], v[208:211], v[100:103]
	v_mfma_f32_16x16x32_bf16 v[92:95], v[156:159], v[216:219], v[92:95]
	v_mfma_f32_16x16x32_bf16 v[84:87], v[164:167], v[216:219], v[84:87]
	v_mfma_f32_16x16x32_bf16 v[76:79], v[156:159], v[224:227], v[76:79]
	v_mfma_f32_16x16x32_bf16 v[68:71], v[164:167], v[224:227], v[68:71]
	v_mfma_f32_16x16x32_bf16 v[124:127], v[160:163], v[204:207], v[124:127]
	v_mfma_f32_16x16x32_bf16 v[116:119], v[180:183], v[204:207], v[116:119]
	v_mfma_f32_16x16x32_bf16 v[108:111], v[160:163], v[212:215], v[108:111]
	v_mfma_f32_16x16x32_bf16 v[100:103], v[180:183], v[212:215], v[100:103]
	v_mfma_f32_16x16x32_bf16 v[92:95], v[160:163], v[220:223], v[92:95]
	v_mfma_f32_16x16x32_bf16 v[84:87], v[180:183], v[220:223], v[84:87]
	v_mfma_f32_16x16x32_bf16 v[76:79], v[160:163], v[228:231], v[76:79]
	v_mfma_f32_16x16x32_bf16 v[68:71], v[180:183], v[228:231], v[68:71]
	s_setprio 0
	s_setprio 1
	v_mfma_f32_16x16x32_bf16 v[120:123], v[184:187], v[200:203], v[120:123]
	v_mfma_f32_16x16x32_bf16 v[112:115], v[192:195], v[200:203], v[112:115]
	v_mfma_f32_16x16x32_bf16 v[104:107], v[184:187], v[208:211], v[104:107]
	v_mfma_f32_16x16x32_bf16 v[96:99], v[192:195], v[208:211], v[96:99]
	v_mfma_f32_16x16x32_bf16 v[88:91], v[184:187], v[216:219], v[88:91]
	v_mfma_f32_16x16x32_bf16 v[80:83], v[192:195], v[216:219], v[80:83]
	v_mfma_f32_16x16x32_bf16 v[72:75], v[184:187], v[224:227], v[72:75]
	v_mfma_f32_16x16x32_bf16 v[64:67], v[192:195], v[224:227], v[64:67]
	v_mfma_f32_16x16x32_bf16 v[120:123], v[188:191], v[204:207], v[120:123]
	v_mfma_f32_16x16x32_bf16 v[112:115], v[196:199], v[204:207], v[112:115]
	v_mfma_f32_16x16x32_bf16 v[104:107], v[188:191], v[212:215], v[104:107]
	v_mfma_f32_16x16x32_bf16 v[96:99], v[196:199], v[212:215], v[96:99]
	v_mfma_f32_16x16x32_bf16 v[88:91], v[188:191], v[220:223], v[88:91]
	v_mfma_f32_16x16x32_bf16 v[80:83], v[196:199], v[220:223], v[80:83]
	v_mfma_f32_16x16x32_bf16 v[72:75], v[188:191], v[228:231], v[72:75]
	v_mfma_f32_16x16x32_bf16 v[64:67], v[196:199], v[228:231], v[64:67]
	s_setprio 0
	s_barrier
	s_add_i32 s9, s10, s63
	s_mov_b32 m0, s9
	ds_read_b128 v[200:203], v154 offset:16384
	ds_read_b128 v[204:207], v154 offset:17408
	ds_read_b128 v[208:211], v154 offset:18432
	ds_read_b128 v[212:215], v154 offset:19456
	ds_read_b128 v[216:219], v154 offset:20480
	ds_read_b128 v[220:223], v154 offset:21504
	ds_read_b128 v[224:227], v154 offset:22528
	ds_read_b128 v[228:231], v154 offset:23552
	global_load_lds_dwordx4 v142, s[58:59]
	s_add_i32 m0, s9, 0x2000
	s_add_u32 s10, s58, 0x40000
	s_addc_u32 s11, s59, 0
	s_add_i32 s5, s5, s63
	global_load_lds_dwordx4 v138, s[58:59]
	s_mov_b32 m0, s5
	s_nop 0
	global_load_lds_dwordx4 v142, s[10:11]
	s_add_i32 m0, s5, 0x2000
	s_nop 0
	global_load_lds_dwordx4 v138, s[10:11]
	s_mov_b32 m0, s66
	s_nop 0
	global_load_lds_dwordx4 v144, s[60:61]
	s_mov_b32 m0, s67
	s_nop 0
	global_load_lds_dwordx4 v140, s[60:61]
	s_waitcnt vmcnt(8)
	s_waitcnt lgkmcnt(0)
	s_barrier
	s_setprio 1
	s_waitcnt lgkmcnt(0)
	v_mfma_f32_16x16x32_bf16 v[60:63], v[156:159], v[200:203], v[60:63]
	v_mfma_f32_16x16x32_bf16 v[52:55], v[164:167], v[200:203], v[52:55]
	v_mfma_f32_16x16x32_bf16 v[44:47], v[156:159], v[208:211], v[44:47]
	v_mfma_f32_16x16x32_bf16 v[36:39], v[164:167], v[208:211], v[36:39]
	v_mfma_f32_16x16x32_bf16 v[28:31], v[156:159], v[216:219], v[28:31]
	v_mfma_f32_16x16x32_bf16 v[20:23], v[164:167], v[216:219], v[20:23]
	v_mfma_f32_16x16x32_bf16 v[12:15], v[156:159], v[224:227], v[12:15]
	v_mfma_f32_16x16x32_bf16 v[4:7], v[164:167], v[224:227], v[4:7]
	v_mfma_f32_16x16x32_bf16 v[60:63], v[160:163], v[204:207], v[60:63]
	v_mfma_f32_16x16x32_bf16 v[52:55], v[180:183], v[204:207], v[52:55]
	v_mfma_f32_16x16x32_bf16 v[44:47], v[160:163], v[212:215], v[44:47]
	v_mfma_f32_16x16x32_bf16 v[36:39], v[180:183], v[212:215], v[36:39]
	v_mfma_f32_16x16x32_bf16 v[28:31], v[160:163], v[220:223], v[28:31]
	v_mfma_f32_16x16x32_bf16 v[20:23], v[180:183], v[220:223], v[20:23]
	v_mfma_f32_16x16x32_bf16 v[12:15], v[160:163], v[228:231], v[12:15]
	v_mfma_f32_16x16x32_bf16 v[4:7], v[180:183], v[228:231], v[4:7]
	s_setprio 0
	s_setprio 1
	v_mfma_f32_16x16x32_bf16 v[56:59], v[184:187], v[200:203], v[56:59]
	v_mfma_f32_16x16x32_bf16 v[48:51], v[192:195], v[200:203], v[48:51]
	v_mfma_f32_16x16x32_bf16 v[40:43], v[184:187], v[208:211], v[40:43]
	v_mfma_f32_16x16x32_bf16 v[32:35], v[192:195], v[208:211], v[32:35]
	v_mfma_f32_16x16x32_bf16 v[24:27], v[184:187], v[216:219], v[24:27]
	v_mfma_f32_16x16x32_bf16 v[16:19], v[192:195], v[216:219], v[16:19]
	v_mfma_f32_16x16x32_bf16 v[8:11], v[184:187], v[224:227], v[8:11]
	v_mfma_f32_16x16x32_bf16 v[0:3], v[192:195], v[224:227], v[0:3]
	v_mfma_f32_16x16x32_bf16 v[56:59], v[188:191], v[204:207], v[56:59]
	v_mfma_f32_16x16x32_bf16 v[48:51], v[196:199], v[204:207], v[48:51]
	v_mfma_f32_16x16x32_bf16 v[40:43], v[188:191], v[212:215], v[40:43]
	v_mfma_f32_16x16x32_bf16 v[32:35], v[196:199], v[212:215], v[32:35]
	v_mfma_f32_16x16x32_bf16 v[24:27], v[188:191], v[220:223], v[24:27]
	v_mfma_f32_16x16x32_bf16 v[16:19], v[196:199], v[220:223], v[16:19]
	v_mfma_f32_16x16x32_bf16 v[8:11], v[188:191], v[228:231], v[8:11]
	v_mfma_f32_16x16x32_bf16 v[0:3], v[196:199], v[228:231], v[0:3]
	s_setprio 0
	s_barrier
; #define PG8_STAGE(bufoff, gbase, voff) do { _Pragma("unroll") for (int _i = 0; _i < 2; ++_i) \
;         __builtin_amdgcn_global_load_lds((const unsigned*)((const char*)(gbase) + (voff)[_i]), (LAS unsigned*)(lds + (bufoff) + ldsw + _i * 8192), 16, 0, 0); } while (0)
; #define PG8_LDA(dst, b, h) do { _Pragma("unroll") for (int m = 0; m < 4; ++m) _Pragma("unroll") for (int k = 0; k < 2; ++k) dst[m][k] = *(const LAS bf16x8*)(lds + PG8_SA(b, h) + aoff + m * 2048 + k * 1024); } while (0)
; #define PG8_LDB(dst, b, h) do { _Pragma("unroll") for (int n = 0; n < 2; ++n) _Pragma("unroll") for (int k = 0; k < 2; ++k) dst[n][k] = *(const LAS bf16x8*)(lds + PG8_SB(b, h) + boff + n * 2048 + k * 1024); } while (0)
; #define PG8_MMA(ai, bj, At, Bt) do { __builtin_amdgcn_s_setprio(1); _Pragma("unroll") for (int m = 0; m < 4; ++m) _Pragma("unroll") for (int n = 0; n < 2; ++n) _Pragma("unroll") for (int k = 0; k < 2; ++k) \
;         acc[ai][bj][m][n] = __builtin_amdgcn_mfma_f32_16x16x32_bf16(Bt[n][k], At[m][k], acc[ai][bj][m][n], 0, 0, 0); __builtin_amdgcn_s_setprio(0); } while (0)
; #define PG8_WAIT_V(n) asm volatile("s_waitcnt vmcnt(" #n ")" ::: "memory")
; #define PG8_WAIT_L(n) asm volatile("s_waitcnt lgkmcnt(" #n ")" ::: "memory")
; #define PG8_BAR __builtin_amdgcn_s_barrier()
; #define PG8_SCHED __builtin_amdgcn_sched_barrier(0)
; template <class Epi, class Sched>
; __device__ __forceinline__ void gemm_phase(LAS unsigned char* lds, const int K, const Sched& S, const Epi& E) {
;     ...
;             PG8_LDB(B0, 1, 0); PG8_LDB(B1, 1, 1); PG8_SCHED; PG8_LDA(At, 1, 0); PG8_STAGE(PG8_SA(0, 1), a2 + hstep, voffA);
;             PG8_WAIT_V(8); PG8_WAIT_L(0); PG8_BAR; PG8_MMA(0, 0, At, B0); PG8_MMA(0, 1, At, B1); PG8_BAR; PG8_SCHED;
;             PG8_LDA(At, 1, 1); PG8_STAGE(PG8_SB(1, 0), b3, voffB); PG8_STAGE(PG8_SB(1, 1), b3 + hstep, voffB); PG8_STAGE(PG8_SA(1, 0), a3, voffA);
;             PG8_WAIT_V(8); PG8_WAIT_L(0); PG8_BAR; PG8_MMA(1, 0, At, B0); PG8_MMA(1, 1, At, B1); PG8_BAR; PG8_SCHED;
	s_add_i32 s5, 0, 0x18000
	v_add_u32_e32 v155, s5, v153
	s_add_i32 s9, 0, 0x1c000
	ds_read_b128 v[156:159], v155
	ds_read_b128 v[160:163], v155 offset:1024
	ds_read_b128 v[164:167], v155 offset:2048
	ds_read_b128 v[180:183], v155 offset:3072
	v_add_u32_e32 v155, s9, v153
	ds_read_b128 v[184:187], v155
	ds_read_b128 v[188:191], v155 offset:1024
	ds_read_b128 v[192:195], v155 offset:2048
	ds_read_b128 v[196:199], v155 offset:3072
	s_add_u32 s10, s60, 0x40000
	s_addc_u32 s11, s61, 0
	s_mov_b32 m0, s68
	ds_read_b128 v[200:203], v154 offset:32768
	ds_read_b128 v[204:207], v154 offset:33792
	ds_read_b128 v[208:211], v154 offset:34816
	ds_read_b128 v[212:215], v154 offset:35840
	ds_read_b128 v[216:219], v154 offset:36864
	ds_read_b128 v[220:223], v154 offset:37888
	ds_read_b128 v[224:227], v154 offset:38912
	ds_read_b128 v[228:231], v154 offset:39936
	global_load_lds_dwordx4 v144, s[10:11]
	s_mov_b32 m0, s69
	s_nop 0
	global_load_lds_dwordx4 v140, s[10:11]
	s_waitcnt vmcnt(8)
	s_waitcnt lgkmcnt(0)
	s_barrier
	s_setprio 1
	s_waitcnt lgkmcnt(0)
	v_mfma_f32_16x16x32_bf16 v[124:127], v[156:159], v[200:203], v[124:127]
	v_mfma_f32_16x16x32_bf16 v[116:119], v[164:167], v[200:203], v[116:119]
	v_mfma_f32_16x16x32_bf16 v[108:111], v[156:159], v[208:211], v[108:111]
	v_mfma_f32_16x16x32_bf16 v[100:103], v[164:167], v[208:211], v[100:103]
	v_mfma_f32_16x16x32_bf16 v[92:95], v[156:159], v[216:219], v[92:95]
	v_mfma_f32_16x16x32_bf16 v[84:87], v[164:167], v[216:219], v[84:87]
	v_mfma_f32_16x16x32_bf16 v[76:79], v[156:159], v[224:227], v[76:79]
	v_mfma_f32_16x16x32_bf16 v[68:71], v[164:167], v[224:227], v[68:71]
	v_mfma_f32_16x16x32_bf16 v[124:127], v[160:163], v[204:207], v[124:127]
	v_mfma_f32_16x16x32_bf16 v[116:119], v[180:183], v[204:207], v[116:119]
	v_mfma_f32_16x16x32_bf16 v[108:111], v[160:163], v[212:215], v[108:111]
	v_mfma_f32_16x16x32_bf16 v[100:103], v[180:183], v[212:215], v[100:103]
	v_mfma_f32_16x16x32_bf16 v[92:95], v[160:163], v[220:223], v[92:95]
	v_mfma_f32_16x16x32_bf16 v[84:87], v[180:183], v[220:223], v[84:87]
	v_mfma_f32_16x16x32_bf16 v[76:79], v[160:163], v[228:231], v[76:79]
	v_mfma_f32_16x16x32_bf16 v[68:71], v[180:183], v[228:231], v[68:71]
	s_setprio 0
	s_setprio 1
	v_mfma_f32_16x16x32_bf16 v[120:123], v[184:187], v[200:203], v[120:123]
	v_mfma_f32_16x16x32_bf16 v[112:115], v[192:195], v[200:203], v[112:115]
	v_mfma_f32_16x16x32_bf16 v[104:107], v[184:187], v[208:211], v[104:107]
	v_mfma_f32_16x16x32_bf16 v[96:99], v[192:195], v[208:211], v[96:99]
	v_mfma_f32_16x16x32_bf16 v[88:91], v[184:187], v[216:219], v[88:91]
	v_mfma_f32_16x16x32_bf16 v[80:83], v[192:195], v[216:219], v[80:83]
	v_mfma_f32_16x16x32_bf16 v[72:75], v[184:187], v[224:227], v[72:75]
	v_mfma_f32_16x16x32_bf16 v[64:67], v[192:195], v[224:227], v[64:67]
	v_mfma_f32_16x16x32_bf16 v[120:123], v[188:191], v[204:207], v[120:123]
	v_mfma_f32_16x16x32_bf16 v[112:115], v[196:199], v[204:207], v[112:115]
	v_mfma_f32_16x16x32_bf16 v[104:107], v[188:191], v[212:215], v[104:107]
	v_mfma_f32_16x16x32_bf16 v[96:99], v[196:199], v[212:215], v[96:99]
	v_mfma_f32_16x16x32_bf16 v[88:91], v[188:191], v[220:223], v[88:91]
	v_mfma_f32_16x16x32_bf16 v[80:83], v[196:199], v[220:223], v[80:83]
	v_mfma_f32_16x16x32_bf16 v[72:75], v[188:191], v[228:231], v[72:75]
	v_mfma_f32_16x16x32_bf16 v[64:67], v[196:199], v[228:231], v[64:67]
	s_setprio 0
	s_barrier
	s_add_i32 s5, s5, s63
	s_mov_b32 m0, s5
	ds_read_b128 v[200:203], v154 offset:49152
	ds_read_b128 v[204:207], v154 offset:50176
	ds_read_b128 v[208:211], v154 offset:51200
	ds_read_b128 v[212:215], v154 offset:52224
	ds_read_b128 v[216:219], v154 offset:53248
	ds_read_b128 v[220:223], v154 offset:54272
	ds_read_b128 v[224:227], v154 offset:55296
	ds_read_b128 v[228:231], v154 offset:56320
	s_add_u32 s100, s58, s36
	s_addc_u32 s101, s59, s37
	global_load_lds_dwordx4 v142, s[100:101]
	s_add_i32 m0, s5, 0x2000
	s_add_u32 s10, s58, 0x40080
	s_addc_u32 s11, s59, 0
	s_add_i32 s5, s9, s63
	s_add_u32 s100, s58, s36
	s_addc_u32 s101, s59, s37
	global_load_lds_dwordx4 v138, s[100:101]
	s_mov_b32 m0, s5
	s_nop 0
	global_load_lds_dwordx4 v142, s[10:11]
	s_add_i32 m0, s5, 0x2000
	s_nop 0
	global_load_lds_dwordx4 v138, s[10:11]
	s_mov_b32 m0, s70
	s_nop 0
	s_add_u32 s100, s60, s36
	s_addc_u32 s101, s61, s37
	global_load_lds_dwordx4 v144, s[100:101]
	s_mov_b32 m0, s71
	s_nop 0
	s_add_u32 s100, s60, s36
	s_addc_u32 s101, s61, s37
	global_load_lds_dwordx4 v140, s[100:101]
	s_waitcnt vmcnt(8)
	s_waitcnt lgkmcnt(0)
	s_barrier
	s_setprio 1
	s_waitcnt lgkmcnt(0)
	v_mfma_f32_16x16x32_bf16 v[60:63], v[156:159], v[200:203], v[60:63]
	v_mfma_f32_16x16x32_bf16 v[52:55], v[164:167], v[200:203], v[52:55]
	v_mfma_f32_16x16x32_bf16 v[44:47], v[156:159], v[208:211], v[44:47]
	v_mfma_f32_16x16x32_bf16 v[36:39], v[164:167], v[208:211], v[36:39]
	v_mfma_f32_16x16x32_bf16 v[28:31], v[156:159], v[216:219], v[28:31]
	v_mfma_f32_16x16x32_bf16 v[20:23], v[164:167], v[216:219], v[20:23]
	v_mfma_f32_16x16x32_bf16 v[12:15], v[156:159], v[224:227], v[12:15]
	v_mfma_f32_16x16x32_bf16 v[4:7], v[164:167], v[224:227], v[4:7]
	v_mfma_f32_16x16x32_bf16 v[60:63], v[160:163], v[204:207], v[60:63]
	v_mfma_f32_16x16x32_bf16 v[52:55], v[180:183], v[204:207], v[52:55]
	v_mfma_f32_16x16x32_bf16 v[44:47], v[160:163], v[212:215], v[44:47]
	v_mfma_f32_16x16x32_bf16 v[36:39], v[180:183], v[212:215], v[36:39]
	v_mfma_f32_16x16x32_bf16 v[28:31], v[160:163], v[220:223], v[28:31]
	v_mfma_f32_16x16x32_bf16 v[20:23], v[180:183], v[220:223], v[20:23]
	v_mfma_f32_16x16x32_bf16 v[12:15], v[160:163], v[228:231], v[12:15]
	v_mfma_f32_16x16x32_bf16 v[4:7], v[180:183], v[228:231], v[4:7]
	s_setprio 0
	s_setprio 1
	v_mfma_f32_16x16x32_bf16 v[56:59], v[184:187], v[200:203], v[56:59]
	v_mfma_f32_16x16x32_bf16 v[48:51], v[192:195], v[200:203], v[48:51]
	v_mfma_f32_16x16x32_bf16 v[40:43], v[184:187], v[208:211], v[40:43]
	v_mfma_f32_16x16x32_bf16 v[32:35], v[192:195], v[208:211], v[32:35]
	v_mfma_f32_16x16x32_bf16 v[24:27], v[184:187], v[216:219], v[24:27]
	v_mfma_f32_16x16x32_bf16 v[16:19], v[192:195], v[216:219], v[16:19]
	v_mfma_f32_16x16x32_bf16 v[8:11], v[184:187], v[224:227], v[8:11]
	v_mfma_f32_16x16x32_bf16 v[0:3], v[192:195], v[224:227], v[0:3]
	v_mfma_f32_16x16x32_bf16 v[56:59], v[188:191], v[204:207], v[56:59]
	v_mfma_f32_16x16x32_bf16 v[48:51], v[196:199], v[204:207], v[48:51]
	v_mfma_f32_16x16x32_bf16 v[40:43], v[188:191], v[212:215], v[40:43]
	v_mfma_f32_16x16x32_bf16 v[32:35], v[196:199], v[212:215], v[32:35]
	v_mfma_f32_16x16x32_bf16 v[24:27], v[188:191], v[220:223], v[24:27]
	v_mfma_f32_16x16x32_bf16 v[16:19], v[196:199], v[220:223], v[16:19]
	v_mfma_f32_16x16x32_bf16 v[8:11], v[188:191], v[228:231], v[8:11]
	v_mfma_f32_16x16x32_bf16 v[0:3], v[196:199], v[228:231], v[0:3]
	s_setprio 0
	s_barrier
	s_add_i32 s4, s4, 2
	s_add_u32 s56, s56, 0x100
	s_addc_u32 s57, s57, 0
	s_add_u32 s1, s1, 0x100
	s_addc_u32 s2, s2, 0
	s_cmp_gt_u32 s4, 13
	s_cbranch_scc0 .LBB0_963
	s_and_b64 vcc, exec, s[46:47]
	s_cbranch_vccz .LBB0_966
	s_barrier

; #define PG8_STAGE(bufoff, gbase, voff) do { _Pragma("unroll") for (int _i = 0; _i < 2; ++_i) \
;         __builtin_amdgcn_global_load_lds((const unsigned*)((const char*)(gbase) + (voff)[_i]), (LAS unsigned*)(lds + (bufoff) + ldsw + _i * 8192), 16, 0, 0); } while (0)
; #define PG8_LDA(dst, b, h) do { _Pragma("unroll") for (int m = 0; m < 4; ++m) _Pragma("unroll") for (int k = 0; k < 2; ++k) dst[m][k] = *(const LAS bf16x8*)(lds + PG8_SA(b, h) + aoff + m * 2048 + k * 1024); } while (0)
; #define PG8_LDB(dst, b, h) do { _Pragma("unroll") for (int n = 0; n < 2; ++n) _Pragma("unroll") for (int k = 0; k < 2; ++k) dst[n][k] = *(const LAS bf16x8*)(lds + PG8_SB(b, h) + boff + n * 2048 + k * 1024); } while (0)
; #define PG8_MMA(ai, bj, At, Bt) do { __builtin_amdgcn_s_setprio(1); _Pragma("unroll") for (int m = 0; m < 4; ++m) _Pragma("unroll") for (int n = 0; n < 2; ++n) _Pragma("unroll") for (int k = 0; k < 2; ++k) \
;         acc[ai][bj][m][n] = __builtin_amdgcn_mfma_f32_16x16x32_bf16(Bt[n][k], At[m][k], acc[ai][bj][m][n], 0, 0, 0); __builtin_amdgcn_s_setprio(0); } while (0)
; #define PG8_WAIT_V(n) asm volatile("s_waitcnt vmcnt(" #n ")" ::: "memory")
; #define PG8_WAIT_L(n) asm volatile("s_waitcnt lgkmcnt(" #n ")" ::: "memory")
; #define PG8_BAR __builtin_amdgcn_s_barrier()
; #define PG8_SCHED __builtin_amdgcn_sched_barrier(0)
; template <class Epi, class Sched>
; __device__ __forceinline__ void gemm_phase(LAS unsigned char* lds, const int K, const Sched& S, const Epi& E) {
;     ...
;             PG8_LDB(B0, 0, 0); PG8_LDB(B1, 0, 1); PG8_SCHED; PG8_LDA(At, 0, 0); PG8_STAGE(PG8_SA(1, 1), a1 + hstep, voffA);
;             PG8_WAIT_V(8); PG8_WAIT_L(0); PG8_BAR; PG8_MMA(0, 0, At, B0); PG8_MMA(0, 1, At, B1); PG8_BAR; PG8_SCHED;
;             PG8_LDA(At, 0, 1); PG8_STAGE(PG8_SB(0, 0), b2, voffB); PG8_STAGE(PG8_SB(0, 1), b2 + hstep, voffB); PG8_STAGE(PG8_SA(0, 0), a2, voffA);
;             PG8_WAIT_V(8); PG8_WAIT_L(0); PG8_BAR; PG8_MMA(1, 0, At, B0); PG8_MMA(1, 1, At, B1); PG8_BAR; PG8_SCHED;
.LBB0_1073:
	s_add_i32 s13, s12, 2
	s_add_u32 s52, s8, 0x100
	s_addc_u32 s53, s9, 0
	s_add_i32 s14, 0, 0x10000
	s_cmp_eq_u32 s5, s12
	s_cselect_b32 s57, s0, s53
	s_cselect_b32 s56, s1, s52
	s_cselect_b32 s55, s2, s11
	s_cselect_b32 s54, s4, s10
	s_add_i32 s12, 0, 0x14000
	v_add_u32_e32 v158, s14, v164
	v_add_u32_e32 v162, s12, v164
	ds_read_b128 v[146:149], v158
	ds_read_b128 v[150:153], v158 offset:1024
	ds_read_b128 v[154:157], v158 offset:2048
	ds_read_b128 v[158:161], v158 offset:3072
	ds_read_b128 v[180:183], v162
	ds_read_b128 v[184:187], v162 offset:1024
	ds_read_b128 v[188:191], v162 offset:2048
	ds_read_b128 v[192:195], v162 offset:3072
	v_lshl_add_u64 v[162:163], s[8:9], 0, v[142:143]
	s_add_i32 m0, s61, 0xc000
	ds_read_b128 v[196:199], v166
	ds_read_b128 v[200:203], v166 offset:1024
	ds_read_b128 v[204:207], v166 offset:2048
	ds_read_b128 v[208:211], v166 offset:3072
	ds_read_b128 v[212:215], v166 offset:4096
	ds_read_b128 v[216:219], v166 offset:5120
	ds_read_b128 v[220:223], v166 offset:6144
	ds_read_b128 v[224:227], v166 offset:7168
	global_load_lds_dwordx4 v[162:163], off
	v_lshl_add_u64 v[162:163], s[8:9], 0, v[144:145]
	s_add_i32 m0, s61, 0xe000
	s_nop 0
	global_load_lds_dwordx4 v[162:163], off
	s_waitcnt vmcnt(8)
	s_waitcnt lgkmcnt(0)
	s_barrier
	s_setprio 1
	s_waitcnt lgkmcnt(0)
	v_mfma_f32_16x16x32_bf16 v[124:127], v[146:149], v[196:199], v[124:127]
	v_mfma_f32_16x16x32_bf16 v[92:95], v[154:157], v[196:199], v[92:95]
	v_mfma_f32_16x16x32_bf16 v[120:123], v[146:149], v[204:207], v[120:123]
	v_mfma_f32_16x16x32_bf16 v[88:91], v[154:157], v[204:207], v[88:91]
	v_mfma_f32_16x16x32_bf16 v[116:119], v[146:149], v[212:215], v[116:119]
	v_mfma_f32_16x16x32_bf16 v[84:87], v[154:157], v[212:215], v[84:87]
	v_mfma_f32_16x16x32_bf16 v[112:115], v[146:149], v[220:223], v[112:115]
	v_mfma_f32_16x16x32_bf16 v[80:83], v[154:157], v[220:223], v[80:83]
	v_mfma_f32_16x16x32_bf16 v[124:127], v[150:153], v[200:203], v[124:127]
	v_mfma_f32_16x16x32_bf16 v[92:95], v[158:161], v[200:203], v[92:95]
	v_mfma_f32_16x16x32_bf16 v[120:123], v[150:153], v[208:211], v[120:123]
	v_mfma_f32_16x16x32_bf16 v[88:91], v[158:161], v[208:211], v[88:91]
	v_mfma_f32_16x16x32_bf16 v[116:119], v[150:153], v[216:219], v[116:119]
	v_mfma_f32_16x16x32_bf16 v[84:87], v[158:161], v[216:219], v[84:87]
	v_mfma_f32_16x16x32_bf16 v[112:115], v[150:153], v[224:227], v[112:115]
	v_mfma_f32_16x16x32_bf16 v[80:83], v[158:161], v[224:227], v[80:83]
	s_setprio 0
	s_setprio 1
	v_mfma_f32_16x16x32_bf16 v[60:63], v[180:183], v[196:199], v[60:63]
	v_mfma_f32_16x16x32_bf16 v[28:31], v[188:191], v[196:199], v[28:31]
	v_mfma_f32_16x16x32_bf16 v[56:59], v[180:183], v[204:207], v[56:59]
	v_mfma_f32_16x16x32_bf16 v[24:27], v[188:191], v[204:207], v[24:27]
	v_mfma_f32_16x16x32_bf16 v[52:55], v[180:183], v[212:215], v[52:55]
	v_mfma_f32_16x16x32_bf16 v[20:23], v[188:191], v[212:215], v[20:23]
	v_mfma_f32_16x16x32_bf16 v[48:51], v[180:183], v[220:223], v[48:51]
	v_mfma_f32_16x16x32_bf16 v[16:19], v[188:191], v[220:223], v[16:19]
	v_mfma_f32_16x16x32_bf16 v[60:63], v[184:187], v[200:203], v[60:63]
	v_mfma_f32_16x16x32_bf16 v[28:31], v[192:195], v[200:203], v[28:31]
	v_mfma_f32_16x16x32_bf16 v[56:59], v[184:187], v[208:211], v[56:59]
	v_mfma_f32_16x16x32_bf16 v[24:27], v[192:195], v[208:211], v[24:27]
	v_mfma_f32_16x16x32_bf16 v[52:55], v[184:187], v[216:219], v[52:55]
	v_mfma_f32_16x16x32_bf16 v[20:23], v[192:195], v[216:219], v[20:23]
	v_mfma_f32_16x16x32_bf16 v[48:51], v[184:187], v[224:227], v[48:51]
	v_mfma_f32_16x16x32_bf16 v[16:19], v[192:195], v[224:227], v[16:19]
	s_setprio 0
	s_barrier
	s_add_i32 s8, s14, s60
	s_mov_b32 m0, s8
	ds_read_b128 v[196:199], v166 offset:16384
	ds_read_b128 v[200:203], v166 offset:17408
	ds_read_b128 v[204:207], v166 offset:18432
	ds_read_b128 v[208:211], v166 offset:19456
	ds_read_b128 v[212:215], v166 offset:20480
	ds_read_b128 v[216:219], v166 offset:21504
	ds_read_b128 v[220:223], v166 offset:22528
	ds_read_b128 v[224:227], v166 offset:23552
	global_load_lds_dwordx4 v128, s[54:55]
	s_add_i32 m0, s8, 0x2000
	s_add_u32 s8, s54, 0xb0000
	s_addc_u32 s9, s55, 0
	s_add_i32 s12, s12, s60
	global_load_lds_dwordx4 v138, s[54:55]
	s_mov_b32 m0, s12
	s_nop 0
	global_load_lds_dwordx4 v128, s[8:9]
	s_add_i32 m0, s12, 0x2000
	s_nop 0
	global_load_lds_dwordx4 v138, s[8:9]
	s_mov_b32 m0, s61
	s_nop 0
	global_load_lds_dwordx4 v128, s[56:57]
	s_mov_b32 m0, s63
	s_nop 0
	global_load_lds_dwordx4 v138, s[56:57]
	s_waitcnt vmcnt(8)
	s_waitcnt lgkmcnt(0)
	s_barrier
; #define PG8_STAGE(bufoff, gbase, voff) do { _Pragma("unroll") for (int _i = 0; _i < 2; ++_i) \
;         __builtin_amdgcn_global_load_lds((const unsigned*)((const char*)(gbase) + (voff)[_i]), (LAS unsigned*)(lds + (bufoff) + ldsw + _i * 8192), 16, 0, 0); } while (0)
; #define PG8_LDA(dst, b, h) do { _Pragma("unroll") for (int m = 0; m < 4; ++m) _Pragma("unroll") for (int k = 0; k < 2; ++k) dst[m][k] = *(const LAS bf16x8*)(lds + PG8_SA(b, h) + aoff + m * 2048 + k * 1024); } while (0)
; #define PG8_LDB(dst, b, h) do { _Pragma("unroll") for (int n = 0; n < 2; ++n) _Pragma("unroll") for (int k = 0; k < 2; ++k) dst[n][k] = *(const LAS bf16x8*)(lds + PG8_SB(b, h) + boff + n * 2048 + k * 1024); } while (0)
; #define PG8_MMA(ai, bj, At, Bt) do { __builtin_amdgcn_s_setprio(1); _Pragma("unroll") for (int m = 0; m < 4; ++m) _Pragma("unroll") for (int n = 0; n < 2; ++n) _Pragma("unroll") for (int k = 0; k < 2; ++k) \
;         acc[ai][bj][m][n] = __builtin_amdgcn_mfma_f32_16x16x32_bf16(Bt[n][k], At[m][k], acc[ai][bj][m][n], 0, 0, 0); __builtin_amdgcn_s_setprio(0); } while (0)
; #define PG8_WAIT_V(n) asm volatile("s_waitcnt vmcnt(" #n ")" ::: "memory")
; #define PG8_WAIT_L(n) asm volatile("s_waitcnt lgkmcnt(" #n ")" ::: "memory")
; #define PG8_BAR __builtin_amdgcn_s_barrier()
; #define PG8_SCHED __builtin_amdgcn_sched_barrier(0)
; template <class Epi, class Sched>
; __device__ __forceinline__ void gemm_phase(LAS unsigned char* lds, const int K, const Sched& S, const Epi& E) {
;     ...
;             PG8_WAIT_V(8); PG8_WAIT_L(0); PG8_BAR; PG8_MMA(1, 0, At, B0); PG8_MMA(1, 1, At, B1); PG8_BAR; PG8_SCHED;
;             PG8_LDB(B0, 1, 0); PG8_LDB(B1, 1, 1); PG8_SCHED; PG8_LDA(At, 1, 0); PG8_STAGE(PG8_SA(0, 1), a2 + hstep, voffA);
;             PG8_WAIT_V(8); PG8_WAIT_L(0); PG8_BAR; PG8_MMA(0, 0, At, B0); PG8_MMA(0, 1, At, B1); PG8_BAR; PG8_SCHED;
;             PG8_LDA(At, 1, 1); PG8_STAGE(PG8_SB(1, 0), b3, voffB); PG8_STAGE(PG8_SB(1, 1), b3 + hstep, voffB); PG8_STAGE(PG8_SA(1, 0), a3, voffA);
	s_setprio 1
	s_waitcnt lgkmcnt(0)
	v_mfma_f32_16x16x32_bf16 v[108:111], v[146:149], v[196:199], v[108:111]
	v_mfma_f32_16x16x32_bf16 v[76:79], v[154:157], v[196:199], v[76:79]
	v_mfma_f32_16x16x32_bf16 v[104:107], v[146:149], v[204:207], v[104:107]
	v_mfma_f32_16x16x32_bf16 v[72:75], v[154:157], v[204:207], v[72:75]
	v_mfma_f32_16x16x32_bf16 v[100:103], v[146:149], v[212:215], v[100:103]
	v_mfma_f32_16x16x32_bf16 v[68:71], v[154:157], v[212:215], v[68:71]
	v_mfma_f32_16x16x32_bf16 v[96:99], v[146:149], v[220:223], v[96:99]
	v_mfma_f32_16x16x32_bf16 v[64:67], v[154:157], v[220:223], v[64:67]
	v_mfma_f32_16x16x32_bf16 v[108:111], v[150:153], v[200:203], v[108:111]
	v_mfma_f32_16x16x32_bf16 v[76:79], v[158:161], v[200:203], v[76:79]
	v_mfma_f32_16x16x32_bf16 v[104:107], v[150:153], v[208:211], v[104:107]
	v_mfma_f32_16x16x32_bf16 v[72:75], v[158:161], v[208:211], v[72:75]
	v_mfma_f32_16x16x32_bf16 v[100:103], v[150:153], v[216:219], v[100:103]
	v_mfma_f32_16x16x32_bf16 v[68:71], v[158:161], v[216:219], v[68:71]
	v_mfma_f32_16x16x32_bf16 v[96:99], v[150:153], v[224:227], v[96:99]
	v_mfma_f32_16x16x32_bf16 v[64:67], v[158:161], v[224:227], v[64:67]
	s_setprio 0
	s_setprio 1
	v_mfma_f32_16x16x32_bf16 v[44:47], v[180:183], v[196:199], v[44:47]
	v_mfma_f32_16x16x32_bf16 v[12:15], v[188:191], v[196:199], v[12:15]
	v_mfma_f32_16x16x32_bf16 v[40:43], v[180:183], v[204:207], v[40:43]
	v_mfma_f32_16x16x32_bf16 v[8:11], v[188:191], v[204:207], v[8:11]
	v_mfma_f32_16x16x32_bf16 v[36:39], v[180:183], v[212:215], v[36:39]
	v_mfma_f32_16x16x32_bf16 v[4:7], v[188:191], v[212:215], v[4:7]
	v_mfma_f32_16x16x32_bf16 v[32:35], v[180:183], v[220:223], v[32:35]
	v_mfma_f32_16x16x32_bf16 v[0:3], v[188:191], v[220:223], v[0:3]
	v_mfma_f32_16x16x32_bf16 v[44:47], v[184:187], v[200:203], v[44:47]
	v_mfma_f32_16x16x32_bf16 v[12:15], v[192:195], v[200:203], v[12:15]
	v_mfma_f32_16x16x32_bf16 v[40:43], v[184:187], v[208:211], v[40:43]
	v_mfma_f32_16x16x32_bf16 v[8:11], v[192:195], v[208:211], v[8:11]
	v_mfma_f32_16x16x32_bf16 v[36:39], v[184:187], v[216:219], v[36:39]
	v_mfma_f32_16x16x32_bf16 v[4:7], v[192:195], v[216:219], v[4:7]
	v_mfma_f32_16x16x32_bf16 v[32:35], v[184:187], v[224:227], v[32:35]
	v_mfma_f32_16x16x32_bf16 v[0:3], v[192:195], v[224:227], v[0:3]
	s_setprio 0
	s_barrier
	s_add_i32 s12, 0, 0x18000
	s_add_i32 s14, 0, 0x1c000
	v_add_u32_e32 v158, s12, v164
	v_add_u32_e32 v167, s14, v164
	ds_read_b128 v[146:149], v158
	ds_read_b128 v[150:153], v158 offset:1024
	ds_read_b128 v[154:157], v158 offset:2048
	ds_read_b128 v[158:161], v158 offset:3072
	ds_read_b128 v[180:183], v167
	ds_read_b128 v[184:187], v167 offset:1024
	ds_read_b128 v[188:191], v167 offset:2048
	ds_read_b128 v[192:195], v167 offset:3072
	s_add_u32 s8, s56, 0xb0000
	s_addc_u32 s9, s57, 0
	s_mov_b32 m0, s64
	ds_read_b128 v[196:199], v166 offset:32768
	ds_read_b128 v[200:203], v166 offset:33792
	ds_read_b128 v[204:207], v166 offset:34816
	ds_read_b128 v[208:211], v166 offset:35840
	ds_read_b128 v[212:215], v166 offset:36864
	ds_read_b128 v[216:219], v166 offset:37888
	ds_read_b128 v[220:223], v166 offset:38912
	ds_read_b128 v[224:227], v166 offset:39936
	global_load_lds_dwordx4 v128, s[8:9]
	s_mov_b32 m0, s65
	s_nop 0
	global_load_lds_dwordx4 v138, s[8:9]
	s_waitcnt vmcnt(8)
	s_waitcnt lgkmcnt(0)
	s_barrier
	s_setprio 1
	s_waitcnt lgkmcnt(0)
	v_mfma_f32_16x16x32_bf16 v[124:127], v[146:149], v[196:199], v[124:127]
	v_mfma_f32_16x16x32_bf16 v[92:95], v[154:157], v[196:199], v[92:95]
	v_mfma_f32_16x16x32_bf16 v[120:123], v[146:149], v[204:207], v[120:123]
	v_mfma_f32_16x16x32_bf16 v[88:91], v[154:157], v[204:207], v[88:91]
	v_mfma_f32_16x16x32_bf16 v[116:119], v[146:149], v[212:215], v[116:119]
	v_mfma_f32_16x16x32_bf16 v[84:87], v[154:157], v[212:215], v[84:87]
	v_mfma_f32_16x16x32_bf16 v[112:115], v[146:149], v[220:223], v[112:115]
	v_mfma_f32_16x16x32_bf16 v[80:83], v[154:157], v[220:223], v[80:83]
	v_mfma_f32_16x16x32_bf16 v[124:127], v[150:153], v[200:203], v[124:127]
	v_mfma_f32_16x16x32_bf16 v[92:95], v[158:161], v[200:203], v[92:95]
	v_mfma_f32_16x16x32_bf16 v[120:123], v[150:153], v[208:211], v[120:123]
	v_mfma_f32_16x16x32_bf16 v[88:91], v[158:161], v[208:211], v[88:91]
	v_mfma_f32_16x16x32_bf16 v[116:119], v[150:153], v[216:219], v[116:119]
	v_mfma_f32_16x16x32_bf16 v[84:87], v[158:161], v[216:219], v[84:87]
	v_mfma_f32_16x16x32_bf16 v[112:115], v[150:153], v[224:227], v[112:115]
	v_mfma_f32_16x16x32_bf16 v[80:83], v[158:161], v[224:227], v[80:83]
	s_setprio 0
	s_setprio 1
	v_mfma_f32_16x16x32_bf16 v[60:63], v[180:183], v[196:199], v[60:63]
	v_mfma_f32_16x16x32_bf16 v[28:31], v[188:191], v[196:199], v[28:31]
	v_mfma_f32_16x16x32_bf16 v[56:59], v[180:183], v[204:207], v[56:59]
	v_mfma_f32_16x16x32_bf16 v[24:27], v[188:191], v[204:207], v[24:27]
	v_mfma_f32_16x16x32_bf16 v[52:55], v[180:183], v[212:215], v[52:55]
	v_mfma_f32_16x16x32_bf16 v[20:23], v[188:191], v[212:215], v[20:23]
	v_mfma_f32_16x16x32_bf16 v[48:51], v[180:183], v[220:223], v[48:51]
	v_mfma_f32_16x16x32_bf16 v[16:19], v[188:191], v[220:223], v[16:19]
	v_mfma_f32_16x16x32_bf16 v[60:63], v[184:187], v[200:203], v[60:63]
	v_mfma_f32_16x16x32_bf16 v[28:31], v[192:195], v[200:203], v[28:31]
	v_mfma_f32_16x16x32_bf16 v[56:59], v[184:187], v[208:211], v[56:59]
	v_mfma_f32_16x16x32_bf16 v[24:27], v[192:195], v[208:211], v[24:27]
	v_mfma_f32_16x16x32_bf16 v[52:55], v[184:187], v[216:219], v[52:55]
	v_mfma_f32_16x16x32_bf16 v[20:23], v[192:195], v[216:219], v[20:23]
	v_mfma_f32_16x16x32_bf16 v[48:51], v[184:187], v[224:227], v[48:51]
	v_mfma_f32_16x16x32_bf16 v[16:19], v[192:195], v[224:227], v[16:19]
	s_setprio 0
	s_barrier
; #define PG8_STAGE(bufoff, gbase, voff) do { _Pragma("unroll") for (int _i = 0; _i < 2; ++_i) \
;         __builtin_amdgcn_global_load_lds((const unsigned*)((const char*)(gbase) + (voff)[_i]), (LAS unsigned*)(lds + (bufoff) + ldsw + _i * 8192), 16, 0, 0); } while (0)
; #define PG8_LDA(dst, b, h) do { _Pragma("unroll") for (int m = 0; m < 4; ++m) _Pragma("unroll") for (int k = 0; k < 2; ++k) dst[m][k] = *(const LAS bf16x8*)(lds + PG8_SA(b, h) + aoff + m * 2048 + k * 1024); } while (0)
; #define PG8_MMA(ai, bj, At, Bt) do { __builtin_amdgcn_s_setprio(1); _Pragma("unroll") for (int m = 0; m < 4; ++m) _Pragma("unroll") for (int n = 0; n < 2; ++n) _Pragma("unroll") for (int k = 0; k < 2; ++k) \
;         acc[ai][bj][m][n] = __builtin_amdgcn_mfma_f32_16x16x32_bf16(Bt[n][k], At[m][k], acc[ai][bj][m][n], 0, 0, 0); __builtin_amdgcn_s_setprio(0); } while (0)
; #define PG8_WAIT_V(n) asm volatile("s_waitcnt vmcnt(" #n ")" ::: "memory")
; #define PG8_WAIT_L(n) asm volatile("s_waitcnt lgkmcnt(" #n ")" ::: "memory")
; #define PG8_BAR __builtin_amdgcn_s_barrier()
; #define PG8_SCHED __builtin_amdgcn_sched_barrier(0)
; template <class Epi, class Sched>
; __device__ __forceinline__ void gemm_phase(LAS unsigned char* lds, const int K, const Sched& S, const Epi& E) {
;     ...
;             PG8_LDA(At, 1, 1); PG8_STAGE(PG8_SB(1, 0), b3, voffB); PG8_STAGE(PG8_SB(1, 1), b3 + hstep, voffB); PG8_STAGE(PG8_SA(1, 0), a3, voffA);
;             PG8_WAIT_V(8); PG8_WAIT_L(0); PG8_BAR; PG8_MMA(1, 0, At, B0); PG8_MMA(1, 1, At, B1); PG8_BAR; PG8_SCHED;
	s_add_i32 s8, s12, s60
	s_mov_b32 m0, s8
	ds_read_b128 v[196:199], v166 offset:49152
	ds_read_b128 v[200:203], v166 offset:50176
	ds_read_b128 v[204:207], v166 offset:51200
	ds_read_b128 v[208:211], v166 offset:52224
	ds_read_b128 v[212:215], v166 offset:53248
	ds_read_b128 v[216:219], v166 offset:54272
	ds_read_b128 v[220:223], v166 offset:55296
	ds_read_b128 v[224:227], v166 offset:56320
	s_add_u32 s100, s54, s36
	s_addc_u32 s101, s55, s37
	global_load_lds_dwordx4 v128, s[100:101]
	s_add_i32 m0, s8, 0x2000
	s_add_u32 s8, s54, 0xb0080
	s_addc_u32 s9, s55, 0
	s_add_i32 s12, s14, s60
	s_add_u32 s100, s54, s36
	s_addc_u32 s101, s55, s37
	global_load_lds_dwordx4 v138, s[100:101]
	s_mov_b32 m0, s12
	s_nop 0
	global_load_lds_dwordx4 v128, s[8:9]
	s_add_i32 m0, s12, 0x2000
	s_nop 0
	global_load_lds_dwordx4 v138, s[8:9]
	s_mov_b32 m0, s68
	s_nop 0
	s_add_u32 s100, s56, s36
	s_addc_u32 s101, s57, s37
	global_load_lds_dwordx4 v128, s[100:101]
	s_mov_b32 m0, s69
	s_nop 0
	s_add_u32 s100, s56, s36
	s_addc_u32 s101, s57, s37
	global_load_lds_dwordx4 v138, s[100:101]
	s_waitcnt vmcnt(8)
	s_waitcnt lgkmcnt(0)
	s_barrier
	s_setprio 1
	s_waitcnt lgkmcnt(0)
	v_mfma_f32_16x16x32_bf16 v[108:111], v[146:149], v[196:199], v[108:111]
	v_mfma_f32_16x16x32_bf16 v[76:79], v[154:157], v[196:199], v[76:79]
	v_mfma_f32_16x16x32_bf16 v[104:107], v[146:149], v[204:207], v[104:107]
	v_mfma_f32_16x16x32_bf16 v[72:75], v[154:157], v[204:207], v[72:75]
	v_mfma_f32_16x16x32_bf16 v[100:103], v[146:149], v[212:215], v[100:103]
	v_mfma_f32_16x16x32_bf16 v[68:71], v[154:157], v[212:215], v[68:71]
	v_mfma_f32_16x16x32_bf16 v[96:99], v[146:149], v[220:223], v[96:99]
	v_mfma_f32_16x16x32_bf16 v[64:67], v[154:157], v[220:223], v[64:67]
	v_mfma_f32_16x16x32_bf16 v[108:111], v[150:153], v[200:203], v[108:111]
	v_mfma_f32_16x16x32_bf16 v[76:79], v[158:161], v[200:203], v[76:79]
	v_mfma_f32_16x16x32_bf16 v[104:107], v[150:153], v[208:211], v[104:107]
	v_mfma_f32_16x16x32_bf16 v[72:75], v[158:161], v[208:211], v[72:75]
	v_mfma_f32_16x16x32_bf16 v[100:103], v[150:153], v[216:219], v[100:103]
	v_mfma_f32_16x16x32_bf16 v[68:71], v[158:161], v[216:219], v[68:71]
	v_mfma_f32_16x16x32_bf16 v[96:99], v[150:153], v[224:227], v[96:99]
	v_mfma_f32_16x16x32_bf16 v[64:67], v[158:161], v[224:227], v[64:67]
	s_setprio 0
	s_setprio 1
	v_mfma_f32_16x16x32_bf16 v[44:47], v[180:183], v[196:199], v[44:47]
	v_mfma_f32_16x16x32_bf16 v[12:15], v[188:191], v[196:199], v[12:15]
	v_mfma_f32_16x16x32_bf16 v[40:43], v[180:183], v[204:207], v[40:43]
	v_mfma_f32_16x16x32_bf16 v[8:11], v[188:191], v[204:207], v[8:11]
	v_mfma_f32_16x16x32_bf16 v[36:39], v[180:183], v[212:215], v[36:39]
	v_mfma_f32_16x16x32_bf16 v[4:7], v[188:191], v[212:215], v[4:7]
	v_mfma_f32_16x16x32_bf16 v[32:35], v[180:183], v[220:223], v[32:35]
	v_mfma_f32_16x16x32_bf16 v[0:3], v[188:191], v[220:223], v[0:3]
	v_mfma_f32_16x16x32_bf16 v[44:47], v[184:187], v[200:203], v[44:47]
	v_mfma_f32_16x16x32_bf16 v[12:15], v[192:195], v[200:203], v[12:15]
	v_mfma_f32_16x16x32_bf16 v[40:43], v[184:187], v[208:211], v[40:43]
	v_mfma_f32_16x16x32_bf16 v[8:11], v[192:195], v[208:211], v[8:11]
	v_mfma_f32_16x16x32_bf16 v[36:39], v[184:187], v[216:219], v[36:39]
	v_mfma_f32_16x16x32_bf16 v[4:7], v[192:195], v[216:219], v[4:7]
	v_mfma_f32_16x16x32_bf16 v[32:35], v[184:187], v[224:227], v[32:35]
	v_mfma_f32_16x16x32_bf16 v[0:3], v[192:195], v[224:227], v[0:3]
	s_setprio 0
	s_barrier
	s_add_u32 s10, s10, 0x100
	s_addc_u32 s11, s11, 0
	s_cmp_ge_i32 s13, s51
	s_mov_b64 s[8:9], s[52:53]
	s_mov_b32 s12, s13
	s_cbranch_scc0 .LBB0_1073
	s_and_b64 vcc, exec, s[40:41]
	s_cbranch_vccz .LBB0_1076

; __global__ void __launch_bounds__(512, 2) mega(Params P) {
	.amdhsa_kernel _Z4mega6Params
		.amdhsa_group_segment_fixed_size 0
		.amdhsa_private_segment_fixed_size 0
		.amdhsa_kernarg_size 432
		.amdhsa_user_sgpr_count 2
		.amdhsa_user_sgpr_dispatch_ptr 0
		.amdhsa_user_sgpr_queue_ptr 0
		.amdhsa_user_sgpr_kernarg_segment_ptr 1
		.amdhsa_user_sgpr_dispatch_id 0
		.amdhsa_user_sgpr_kernarg_preload_length 0
		.amdhsa_user_sgpr_kernarg_preload_offset 0
		.amdhsa_user_sgpr_private_segment_size 0
		.amdhsa_uses_dynamic_stack 0
		.amdhsa_enable_private_segment 0
		.amdhsa_system_sgpr_workgroup_id_x 1
		.amdhsa_system_sgpr_workgroup_id_y 0
		.amdhsa_system_sgpr_workgroup_id_z 0
		.amdhsa_system_sgpr_workgroup_info 0
		.amdhsa_system_vgpr_workitem_id 2
		.amdhsa_next_free_vgpr 256
		.amdhsa_next_free_sgpr 102
		.amdhsa_accum_offset 256
		.amdhsa_reserve_vcc 1
		.amdhsa_float_round_mode_32 0
		.amdhsa_float_round_mode_16_64 0
		.amdhsa_float_denorm_mode_32 3
		.amdhsa_float_denorm_mode_16_64 3
		.amdhsa_dx10_clamp 1
		.amdhsa_ieee_mode 1
		.amdhsa_fp16_overflow 0
		.amdhsa_tg_split 0
		.amdhsa_exception_fp_ieee_invalid_op 0
		.amdhsa_exception_fp_denorm_src 0
		.amdhsa_exception_fp_ieee_div_zero 0
		.amdhsa_exception_fp_ieee_overflow 0
		.amdhsa_exception_fp_ieee_underflow 0
		.amdhsa_exception_fp_ieee_inexact 0
		.amdhsa_exception_int_div_zero 0
	.end_amdhsa_kernel

; __global__ void __launch_bounds__(512, 2) mega(Params P) {
amdhsa.kernels:
  - .agpr_count:     0
    .args:
      - .offset:         0
        .size:           176
        .value_kind:     by_value
      - .offset:         176
        .size:           4
        .value_kind:     hidden_block_count_x
      - .offset:         180
        .size:           4
        .value_kind:     hidden_block_count_y
      - .offset:         184
        .size:           4
        .value_kind:     hidden_block_count_z
      - .offset:         188
        .size:           2
        .value_kind:     hidden_group_size_x
      - .offset:         190
        .size:           2
        .value_kind:     hidden_group_size_y
      - .offset:         192
        .size:           2
        .value_kind:     hidden_group_size_z
      - .offset:         194
        .size:           2
        .value_kind:     hidden_remainder_x
      - .offset:         196
        .size:           2
        .value_kind:     hidden_remainder_y
      - .offset:         198
        .size:           2
        .value_kind:     hidden_remainder_z
      - .offset:         216
        .size:           8
        .value_kind:     hidden_global_offset_x
      - .offset:         224
        .size:           8
        .value_kind:     hidden_global_offset_y
      - .offset:         232
        .size:           8
        .value_kind:     hidden_global_offset_z
      - .offset:         240
        .size:           2
        .value_kind:     hidden_grid_dims
      - .offset:         264
        .size:           8
        .value_kind:     hidden_multigrid_sync_arg
      - .offset:         296
        .size:           4
        .value_kind:     hidden_dynamic_lds_size
    .group_segment_fixed_size: 0
    .kernarg_segment_align: 8
    .kernarg_segment_size: 432
    .language:       OpenCL C
    .language_version:
      - 2
      - 0
    .max_flat_workgroup_size: 512
    .name:           _Z4mega6Params
    .private_segment_fixed_size: 0
    .sgpr_count:     108
    .sgpr_spill_count: 375
    .symbol:         _Z4mega6Params.kd
    .uniform_work_group_size: 1
    .uses_dynamic_stack: false
    .vgpr_count:     256
    .vgpr_spill_count: 0
    .wavefront_size: 64
